# first phase: streaming (nt) hint on the once-read modulation-weight loads and the input-projection weight conversion DMA loads
# speedup vs baseline: 1.0085x; 1.0085x over previous
.LBB0_9:
	s_or_b64 exec, exec, s[4:5]
	s_load_dwordx2 s[2:3], s[38:39], 0xc8
	s_load_dword s1, s[38:39], 0xd0
	v_readlane_b32 s0, v255, 0
	s_lshr_b32 s4, s0, 6
	s_lshl_b32 s0, s96, 3
	v_writelane_b32 v255, s4, 12
	s_waitcnt lgkmcnt(0)
	s_lshl_b32 s14, s1, 3
	s_add_i32 s4, s0, s4
	s_cmp_lt_i32 s2, 1
	s_cselect_b64 s[0:1], -1, 0
	v_writelane_b32 v255, s2, 13
	s_cmp_gt_i32 s3, 0
	v_and_b32_e32 v210, 63, v0
	v_writelane_b32 v255, s3, 14
	s_cselect_b64 s[2:3], -1, 0
	s_and_b64 s[8:9], s[0:1], s[2:3]
	s_mov_b32 s0, s14
	v_writelane_b32 v255, s0, 15
	s_andn2_b64 vcc, exec, s[8:9]
	s_nop 0
	v_writelane_b32 v255, s1, 16
	s_mov_b32 s0, s4
	v_writelane_b32 v255, s0, 17
	s_nop 1
	v_writelane_b32 v255, s1, 18
	v_writelane_b32 v255, s38, 19
	s_mov_b32 s0, s96
	s_nop 0
	v_writelane_b32 v255, s39, 20
	v_writelane_b32 v255, s0, 21
	s_nop 1
	v_writelane_b32 v255, s1, 22
	s_cbranch_vccnz .LBB0_161
	v_writelane_b32 v255, s8, 23
	v_lshlrev_b32_e32 v78, 2, v0
	v_mov_b32_e32 v79, 0
	v_writelane_b32 v255, s9, 24
	s_load_dwordx4 s[8:11], s[38:39], 0x8
	s_load_dwordx2 s[0:1], s[38:39], 0xc0
	s_waitcnt lgkmcnt(0)
	global_load_dword v1, v78, s[8:9]
	global_load_dword v12, v78, s[8:9] offset:2048
	v_lshl_add_u64 v[2:3], s[8:9], 0, v[78:79]
	v_add_co_u32_e32 v4, vcc, 0x1000, v2
	v_writelane_b32 v255, s0, 25
	s_nop 0
	v_addc_co_u32_e32 v5, vcc, 0, v3, vcc
	v_add_co_u32_e32 v6, vcc, 0x2000, v2
	v_writelane_b32 v255, s1, 26
	s_nop 0
	v_addc_co_u32_e32 v7, vcc, 0, v3, vcc
	v_add_co_u32_e32 v8, vcc, 0x3000, v2
	s_mov_b64 s[2:3], s[10:11]
	s_nop 0
	v_addc_co_u32_e32 v9, vcc, 0, v3, vcc
	v_add_co_u32_e32 v10, vcc, 0x4000, v2
	v_writelane_b32 v255, s0, 27
	s_nop 0
	v_addc_co_u32_e32 v11, vcc, 0, v3, vcc
	global_load_dword v13, v[4:5], off nt
	global_load_dword v14, v[4:5], off offset:2048 nt
	global_load_dword v15, v[6:7], off nt
	global_load_dword v16, v[6:7], off offset:2048 nt
	global_load_dword v17, v[8:9], off nt
	global_load_dword v18, v[8:9], off offset:2048 nt
	global_load_dword v19, v[10:11], off nt
	global_load_dword v20, v[10:11], off offset:2048 nt
	v_add_co_u32_e32 v4, vcc, 0x5000, v2
	v_writelane_b32 v255, s1, 28
	s_nop 0
	v_addc_co_u32_e32 v5, vcc, 0, v3, vcc
	v_add_co_u32_e32 v6, vcc, 0x6000, v2
	v_writelane_b32 v255, s2, 29
	s_nop 0
	v_addc_co_u32_e32 v7, vcc, 0, v3, vcc
	v_add_co_u32_e32 v8, vcc, 0x7000, v2
	v_writelane_b32 v255, s3, 30
	s_nop 0
	v_addc_co_u32_e32 v9, vcc, 0, v3, vcc
	v_add_co_u32_e32 v10, vcc, 0x8000, v2
	s_cmpk_gt_i32 s4, 0x5ff
	s_nop 0
	v_addc_co_u32_e32 v11, vcc, 0, v3, vcc
	global_load_dword v21, v[4:5], off nt
	global_load_dword v22, v[4:5], off offset:2048 nt
	global_load_dword v23, v[6:7], off nt
	global_load_dword v24, v[6:7], off offset:2048 nt
	global_load_dword v25, v[8:9], off nt
	global_load_dword v26, v[8:9], off offset:2048 nt
	global_load_dword v27, v[10:11], off nt
	global_load_dword v28, v[10:11], off offset:2048 nt
	v_add_co_u32_e32 v4, vcc, 0x9000, v2
	s_nop 1
	v_addc_co_u32_e32 v5, vcc, 0, v3, vcc
	v_add_co_u32_e32 v6, vcc, 0xa000, v2
	s_nop 1
	v_addc_co_u32_e32 v7, vcc, 0, v3, vcc
	v_add_co_u32_e32 v8, vcc, 0xb000, v2
	s_nop 1
	v_addc_co_u32_e32 v9, vcc, 0, v3, vcc
	v_add_co_u32_e32 v10, vcc, 0xc000, v2
	s_nop 1
	v_addc_co_u32_e32 v11, vcc, 0, v3, vcc
	global_load_dword v29, v[4:5], off nt
	global_load_dword v30, v[4:5], off offset:2048 nt
	global_load_dword v31, v[6:7], off nt
	global_load_dword v32, v[6:7], off offset:2048 nt
	global_load_dword v33, v[8:9], off nt
	global_load_dword v34, v[8:9], off offset:2048 nt
	global_load_dword v35, v[10:11], off nt
	global_load_dword v36, v[10:11], off offset:2048 nt
	v_add_co_u32_e32 v4, vcc, 0xd000, v2
	s_nop 1
	v_addc_co_u32_e32 v5, vcc, 0, v3, vcc
	v_add_co_u32_e32 v6, vcc, 0xe000, v2
	s_nop 1
	v_addc_co_u32_e32 v7, vcc, 0, v3, vcc
	v_add_co_u32_e32 v2, vcc, 0xf000, v2
	s_nop 1
	v_addc_co_u32_e32 v3, vcc, 0, v3, vcc
	global_load_dword v8, v[4:5], off nt
	global_load_dword v9, v[4:5], off offset:2048 nt
	global_load_dword v10, v[6:7], off nt
	global_load_dword v11, v[6:7], off offset:2048 nt
	global_load_dword v37, v[2:3], off nt
	global_load_dword v38, v[2:3], off offset:2048 nt
	s_waitcnt vmcnt(31)
	v_mul_f32_e32 v2, 0xbfb8aa3b, v1
	s_waitcnt vmcnt(30)
	v_mul_f32_e32 v3, 0xbfb8aa3b, v12
	v_exp_f32_e32 v2, v2
	v_exp_f32_e32 v3, v3
	v_add_u32_e32 v4, 0, v78
	v_add_f32_e32 v2, 1.0, v2
	v_add_f32_e32 v3, 1.0, v3
	v_rcp_f32_e32 v2, v2
	v_rcp_f32_e32 v3, v3
	v_mul_f32_e32 v1, v1, v2
	v_mul_f32_e32 v2, v12, v3
	s_waitcnt vmcnt(29)
	v_mul_f32_e32 v5, 0xbfb8aa3b, v13
	ds_write2st64_b32 v4, v1, v2 offset1:8
	s_waitcnt vmcnt(28)
	v_mul_f32_e32 v2, 0xbfb8aa3b, v14
	v_exp_f32_e32 v5, v5
	v_exp_f32_e32 v2, v2
	s_waitcnt vmcnt(27)
	v_mul_f32_e32 v3, 0xbfb8aa3b, v15
	v_exp_f32_e32 v3, v3
	v_add_f32_e32 v1, 1.0, v5
	v_add_f32_e32 v2, 1.0, v2
	v_rcp_f32_e32 v1, v1
	v_rcp_f32_e32 v2, v2
	v_add_f32_e32 v3, 1.0, v3
	s_waitcnt vmcnt(26)
	v_mul_f32_e32 v5, 0xbfb8aa3b, v16
	v_rcp_f32_e32 v3, v3
	v_exp_f32_e32 v5, v5
	v_mul_f32_e32 v1, v13, v1
	v_mul_f32_e32 v2, v14, v2
	ds_write2st64_b32 v4, v1, v2 offset0:16 offset1:24
	v_mul_f32_e32 v1, v15, v3
	v_add_f32_e32 v2, 1.0, v5
	s_waitcnt vmcnt(25)
	v_mul_f32_e32 v3, 0xbfb8aa3b, v17
	s_waitcnt vmcnt(24)
	v_mul_f32_e32 v5, 0xbfb8aa3b, v18
	v_exp_f32_e32 v3, v3
	v_exp_f32_e32 v5, v5
	v_rcp_f32_e32 v2, v2
	v_add_f32_e32 v3, 1.0, v3
	v_add_f32_e32 v5, 1.0, v5
	v_rcp_f32_e32 v3, v3
	v_rcp_f32_e32 v5, v5
	v_mul_f32_e32 v2, v16, v2
	ds_write2st64_b32 v4, v1, v2 offset0:32 offset1:40
	v_mul_f32_e32 v1, v17, v3
	v_mul_f32_e32 v2, v18, v5
	s_waitcnt vmcnt(23)
	v_mul_f32_e32 v3, 0xbfb8aa3b, v19
	s_waitcnt vmcnt(22)
	v_mul_f32_e32 v5, 0xbfb8aa3b, v20
	v_exp_f32_e32 v3, v3
	v_exp_f32_e32 v5, v5
	ds_write2st64_b32 v4, v1, v2 offset0:48 offset1:56
	v_add_f32_e32 v1, 1.0, v3
	v_add_f32_e32 v2, 1.0, v5
	v_rcp_f32_e32 v1, v1
	v_rcp_f32_e32 v2, v2
	s_waitcnt vmcnt(21)
	v_mul_f32_e32 v3, 0xbfb8aa3b, v21
	v_exp_f32_e32 v3, v3
	v_mul_f32_e32 v1, v19, v1
	v_mul_f32_e32 v2, v20, v2
	ds_write2st64_b32 v4, v1, v2 offset0:64 offset1:72
	s_waitcnt vmcnt(20)
	v_mul_f32_e32 v2, 0xbfb8aa3b, v22
	v_add_f32_e32 v1, 1.0, v3
	v_exp_f32_e32 v2, v2
	s_waitcnt vmcnt(19)
	v_mul_f32_e32 v3, 0xbfb8aa3b, v23
	v_exp_f32_e32 v3, v3
	v_rcp_f32_e32 v1, v1
	v_add_f32_e32 v2, 1.0, v2
	v_rcp_f32_e32 v2, v2
	v_add_f32_e32 v3, 1.0, v3
	s_waitcnt vmcnt(18)
	v_mul_f32_e32 v5, 0xbfb8aa3b, v24
	v_rcp_f32_e32 v3, v3
	v_exp_f32_e32 v5, v5
	v_mul_f32_e32 v1, v21, v1
	v_mul_f32_e32 v2, v22, v2
	ds_write2st64_b32 v4, v1, v2 offset0:80 offset1:88
	v_mul_f32_e32 v1, v23, v3
	v_add_f32_e32 v2, 1.0, v5
	s_waitcnt vmcnt(17)
	v_mul_f32_e32 v3, 0xbfb8aa3b, v25
	s_waitcnt vmcnt(16)
	v_mul_f32_e32 v5, 0xbfb8aa3b, v26
	v_exp_f32_e32 v3, v3
	v_exp_f32_e32 v5, v5
	v_rcp_f32_e32 v2, v2
	v_add_f32_e32 v3, 1.0, v3
	v_add_f32_e32 v5, 1.0, v5
	v_rcp_f32_e32 v3, v3
	v_rcp_f32_e32 v5, v5
	v_mul_f32_e32 v2, v24, v2
	ds_write2st64_b32 v4, v1, v2 offset0:96 offset1:104
	v_mul_f32_e32 v1, v25, v3
	v_mul_f32_e32 v2, v26, v5
	s_waitcnt vmcnt(15)
	v_mul_f32_e32 v3, 0xbfb8aa3b, v27
	s_waitcnt vmcnt(14)
	v_mul_f32_e32 v5, 0xbfb8aa3b, v28
	v_exp_f32_e32 v3, v3
	v_exp_f32_e32 v5, v5
	ds_write2st64_b32 v4, v1, v2 offset0:112 offset1:120
	v_add_f32_e32 v1, 1.0, v3
	v_add_f32_e32 v2, 1.0, v5
	v_rcp_f32_e32 v1, v1
	v_rcp_f32_e32 v2, v2
	s_waitcnt vmcnt(13)
	v_mul_f32_e32 v3, 0xbfb8aa3b, v29
	v_exp_f32_e32 v3, v3
	v_mul_f32_e32 v1, v27, v1
	v_mul_f32_e32 v2, v28, v2
	ds_write2st64_b32 v4, v1, v2 offset0:128 offset1:136
	s_waitcnt vmcnt(12)
	v_mul_f32_e32 v2, 0xbfb8aa3b, v30
	v_add_f32_e32 v1, 1.0, v3
	v_exp_f32_e32 v2, v2
	s_waitcnt vmcnt(11)
	v_mul_f32_e32 v3, 0xbfb8aa3b, v31
	v_exp_f32_e32 v3, v3
	v_rcp_f32_e32 v1, v1
	v_add_f32_e32 v2, 1.0, v2
	v_rcp_f32_e32 v2, v2
	v_add_f32_e32 v3, 1.0, v3
	s_waitcnt vmcnt(10)
	v_mul_f32_e32 v5, 0xbfb8aa3b, v32
	v_rcp_f32_e32 v3, v3
	v_exp_f32_e32 v5, v5
	v_mul_f32_e32 v1, v29, v1
	v_mul_f32_e32 v2, v30, v2
	ds_write2st64_b32 v4, v1, v2 offset0:144 offset1:152
	v_mul_f32_e32 v1, v31, v3
	v_add_f32_e32 v2, 1.0, v5
	s_waitcnt vmcnt(9)
	v_mul_f32_e32 v3, 0xbfb8aa3b, v33
	s_waitcnt vmcnt(8)
	v_mul_f32_e32 v5, 0xbfb8aa3b, v34
	v_exp_f32_e32 v3, v3
	v_exp_f32_e32 v5, v5
	v_rcp_f32_e32 v2, v2
	v_add_f32_e32 v3, 1.0, v3
	v_add_f32_e32 v5, 1.0, v5
	v_rcp_f32_e32 v3, v3
	v_rcp_f32_e32 v5, v5
	v_mul_f32_e32 v2, v32, v2
	ds_write2st64_b32 v4, v1, v2 offset0:160 offset1:168
	v_mul_f32_e32 v1, v33, v3
	v_mul_f32_e32 v2, v34, v5
	s_waitcnt vmcnt(7)
	v_mul_f32_e32 v3, 0xbfb8aa3b, v35
	s_waitcnt vmcnt(6)
	v_mul_f32_e32 v5, 0xbfb8aa3b, v36
	v_exp_f32_e32 v3, v3
	v_exp_f32_e32 v5, v5
	ds_write2st64_b32 v4, v1, v2 offset0:176 offset1:184
	v_add_f32_e32 v1, 1.0, v3
	v_add_f32_e32 v2, 1.0, v5
	v_rcp_f32_e32 v1, v1
	v_rcp_f32_e32 v2, v2
	s_waitcnt vmcnt(5)
	v_mul_f32_e32 v3, 0xbfb8aa3b, v8
	v_exp_f32_e32 v3, v3
	v_mul_f32_e32 v1, v35, v1
	v_mul_f32_e32 v2, v36, v2
	ds_write2st64_b32 v4, v1, v2 offset0:192 offset1:200
	s_waitcnt vmcnt(4)
	v_mul_f32_e32 v2, 0xbfb8aa3b, v9
	v_add_f32_e32 v1, 1.0, v3
	v_exp_f32_e32 v2, v2
	s_waitcnt vmcnt(3)
	v_mul_f32_e32 v3, 0xbfb8aa3b, v10
	v_exp_f32_e32 v3, v3
	v_rcp_f32_e32 v1, v1
	v_add_f32_e32 v2, 1.0, v2
	v_rcp_f32_e32 v2, v2
	v_add_f32_e32 v3, 1.0, v3
	s_waitcnt vmcnt(2)
	v_mul_f32_e32 v5, 0xbfb8aa3b, v11
	v_rcp_f32_e32 v3, v3
	v_exp_f32_e32 v5, v5
	v_mul_f32_e32 v1, v8, v1
	v_mul_f32_e32 v2, v9, v2
	ds_write2st64_b32 v4, v1, v2 offset0:208 offset1:216
	v_mul_f32_e32 v1, v10, v3
	v_add_f32_e32 v2, 1.0, v5
	s_waitcnt vmcnt(1)
	v_mul_f32_e32 v3, 0xbfb8aa3b, v37
	s_waitcnt vmcnt(0)
	v_mul_f32_e32 v5, 0xbfb8aa3b, v38
	v_exp_f32_e32 v3, v3
	v_exp_f32_e32 v5, v5
	v_rcp_f32_e32 v2, v2
	v_add_f32_e32 v3, 1.0, v3
	v_add_f32_e32 v5, 1.0, v5
	v_rcp_f32_e32 v3, v3
	v_rcp_f32_e32 v5, v5
	v_mul_f32_e32 v2, v11, v2
	ds_write2st64_b32 v4, v1, v2 offset0:224 offset1:232
	v_mul_f32_e32 v1, v37, v3
	v_mul_f32_e32 v2, v38, v5
	ds_write2st64_b32 v4, v1, v2 offset0:240 offset1:248
	s_waitcnt lgkmcnt(0)
	s_barrier
	s_cbranch_scc1 .LBB0_15
	v_readlane_b32 s0, v255, 25
	v_readlane_b32 s1, v255, 26
	s_add_u32 s0, s0, 0x100000
	s_addc_u32 s1, s1, 0
	v_writelane_b32 v255, s0, 31
	v_mov_b32_e32 v1, 0xc000
	v_mov_b32_e32 v77, 0x60000
	v_writelane_b32 v255, s1, 32
	s_nop 0
	v_readlane_b32 s0, v255, 17
	s_mov_b32 s12, s0
	v_readlane_b32 s1, v255, 18

.LBB0_13:
	s_or_b32 s14, s92, s16
	s_or_b32 s33, s92, s18
	s_or_b32 s34, s92, s19
	s_or_b32 s36, s92, s20
	s_or_b32 s7, s92, s21
	s_or_b32 s11, s92, s23
	s_or_b32 s10, s92, s24
	s_or_b32 s9, s92, s25
	s_or_b32 s35, s92, s22
	s_or_b32 s41, s92, s26
	s_or_b32 s6, s92, s27
	s_or_b32 s5, s92, s28
	s_or_b32 s8, s92, s31
	s_or_b32 s3, s92, s42
	s_or_b32 s1, s92, s43
	s_or_b32 s94, s92, s44
	v_mad_i64_i32 v[10:11], s[38:39], s14, v1, v[82:83]
	v_mad_i64_i32 v[12:13], s[38:39], s33, v1, v[82:83]
	s_or_b32 s33, s92, s50
	v_mad_i64_i32 v[14:15], s[38:39], s34, v1, v[82:83]
	v_mad_i64_i32 v[16:17], s[38:39], s36, v1, v[82:83]
	s_or_b32 s36, s92, s52
	v_mad_i64_i32 v[18:19], s[38:39], s7, v1, v[82:83]
	v_mad_i64_i32 v[22:23], s[96:97], s11, v1, v[82:83]
	v_mad_i64_i32 v[24:25], s[10:11], s10, v1, v[82:83]
	v_mad_i64_i32 v[26:27], s[10:11], s9, v1, v[82:83]
	s_or_b32 s4, s92, s29
	s_or_b32 s15, s92, s30
	s_or_b32 s93, s92, s45
	s_or_b32 s2, s92, s47
	s_or_b32 s37, s92, s48
	s_or_b32 s14, s92, s49
	s_or_b32 s34, s92, s51
	s_or_b32 s39, s92, s53
	v_mad_i64_i32 v[20:21], s[96:97], s35, v1, v[82:83]
	s_or_b32 s38, s92, s54
	s_or_b32 s7, s92, s55
	s_or_b32 s40, s92, s56
	s_or_b32 s10, s92, s57
	v_mad_i64_i32 v[28:29], s[96:97], s41, v1, v[82:83]
	s_or_b32 s11, s92, s58
	v_mad_i64_i32 v[30:31], s[96:97], s6, v1, v[82:83]
	s_or_b32 s35, s92, s59
	v_mad_i64_i32 v[32:33], s[96:97], s5, v1, v[82:83]
	v_mad_i64_i32 v[40:41], s[96:97], s8, v1, v[82:83]
	v_mad_i64_i32 v[42:43], s[96:97], s3, v1, v[82:83]
	v_mad_i64_i32 v[44:45], s[96:97], s1, v1, v[82:83]
	v_mad_i64_i32 v[46:47], s[94:95], s94, v1, v[82:83]
	v_mad_i64_i32 v[64:65], s[96:97], s33, v1, v[82:83]
	v_mad_i64_i32 v[68:69], s[96:97], s36, v1, v[82:83]
	v_mad_i64_i32 v[36:37], s[4:5], s4, v1, v[82:83]
	v_mad_i64_i32 v[38:39], s[4:5], s15, v1, v[82:83]
	v_mad_i64_i32 v[50:51], s[96:97], s93, v1, v[82:83]
	v_mad_i64_i32 v[52:53], s[2:3], s2, v1, v[82:83]
	v_mad_i64_i32 v[60:61], s[96:97], s37, v1, v[82:83]
	v_mad_i64_i32 v[62:63], s[96:97], s14, v1, v[82:83]
	v_mad_i64_i32 v[66:67], s[96:97], s34, v1, v[82:83]
	v_mad_i64_i32 v[70:71], s[96:97], s39, v1, v[82:83]
	v_mad_i64_i32 v[72:73], s[38:39], s38, v1, v[82:83]
	v_mad_i64_i32 v[74:75], s[96:97], s7, v1, v[82:83]
	v_mad_i64_i32 v[86:87], s[96:97], s40, v1, v[82:83]
	v_mad_i64_i32 v[88:89], s[96:97], s10, v1, v[82:83]
	v_mad_i64_i32 v[90:91], s[10:11], s11, v1, v[82:83]
	v_mad_i64_i32 v[92:93], s[10:11], s35, v1, v[82:83]
	global_load_dword v134, v[10:11], off nt
	global_load_dword v136, v[12:13], off nt
	global_load_dword v138, v[14:15], off nt
	global_load_dword v140, v[16:17], off nt
	global_load_dword v142, v[18:19], off nt
	global_load_dword v144, v[20:21], off nt
	global_load_dword v146, v[22:23], off nt
	global_load_dword v148, v[24:25], off nt
	global_load_dword v150, v[26:27], off nt
	global_load_dword v152, v[28:29], off nt
	global_load_dword v154, v[30:31], off nt
	s_nop 0
	global_load_dword v32, v[32:33], off nt
	s_nop 0
	global_load_dword v156, v[36:37], off nt
	global_load_dword v158, v[38:39], off nt
	global_load_dword v160, v[40:41], off nt
	s_nop 0
	global_load_dword v42, v[42:43], off nt
	s_nop 0
	global_load_dword v24, v[44:45], off nt
	global_load_dword v20, v[46:47], off nt
	global_load_dword v18, v[50:51], off nt
	global_load_dword v16, v[52:53], off nt
	global_load_dword v14, v[60:61], off nt
	global_load_dword v12, v[62:63], off nt
	global_load_dword v10, v[64:65], off nt
	global_load_dword v22, v[66:67], off nt
	global_load_dword v30, v[68:69], off nt
	global_load_dword v28, v[70:71], off nt
	global_load_dword v26, v[72:73], off nt
	global_load_dword v40, v[74:75], off nt
	global_load_dword v46, v[86:87], off nt
	global_load_dword v44, v[88:89], off nt
	global_load_dword v64, v[90:91], off nt
	global_load_dword v68, v[92:93], off nt
	s_lshl_b32 s0, s92, 2
	s_or_b32 s9, s92, s60
	s_add_i32 s0, s17, s0
	s_or_b32 s41, s92, s61
	v_mad_i64_i32 v[58:59], s[10:11], s9, v1, v[82:83]
	v_mov_b32_e32 v79, s0
	s_or_b32 s4, s92, s62
	v_mad_i64_i32 v[56:57], s[10:11], s41, v1, v[82:83]
	ds_read_b128 v[36:39], v79
	ds_read_b128 v[50:53], v79 offset:16
	ds_read_b128 v[60:63], v79 offset:40960
	ds_read_b128 v[70:73], v79 offset:8192
	ds_read_b128 v[86:89], v79 offset:8208
	ds_read_b128 v[90:93], v79 offset:16384
	ds_read_b128 v[94:97], v79 offset:16400
	ds_read_b128 v[98:101], v79 offset:24576
	ds_read_b128 v[102:105], v79 offset:24592
	ds_read_b128 v[106:109], v79 offset:32768
	ds_read_b128 v[110:113], v79 offset:32784
	ds_read_b128 v[114:117], v79 offset:40976
	ds_read_b128 v[118:121], v79 offset:49152
	ds_read_b128 v[122:125], v79 offset:49168
	ds_read_b128 v[126:129], v79 offset:57344
	ds_read_b128 v[130:133], v79 offset:57360
	global_load_dword v58, v[58:59], off nt
	v_mad_i64_i32 v[54:55], s[10:11], s4, v1, v[82:83]
	global_load_dword v56, v[56:57], off nt
	s_waitcnt lgkmcnt(14)
	v_mov_b32_e32 v66, v36
	global_load_dword v54, v[54:55], off nt
	s_waitcnt lgkmcnt(12)
	v_mov_b32_e32 v67, v70
	s_waitcnt lgkmcnt(10)
	v_mov_b32_e32 v162, v90
	s_waitcnt lgkmcnt(8)
	v_mov_b32_e32 v163, v98
	v_mov_b32_e32 v98, v91
	v_mov_b32_e32 v164, v92
	v_mov_b32_e32 v165, v100
	v_mov_b32_e32 v100, v93
	s_waitcnt lgkmcnt(6)
	v_mov_b32_e32 v90, v106
	v_mov_b32_e32 v91, v60
	s_waitcnt lgkmcnt(3)
	v_mov_b32_e32 v92, v118
	s_waitcnt lgkmcnt(1)
	v_mov_b32_e32 v93, v126
	v_mov_b32_e32 v70, v37
	v_mov_b32_e32 v60, v107
	v_mov_b32_e32 v126, v119
	v_mov_b32_e32 v166, v108
	v_mov_b32_e32 v167, v62
	v_mov_b32_e32 v118, v120
	v_mov_b32_e32 v119, v128
	v_mov_b32_e32 v74, v38
	v_mov_b32_e32 v75, v72
	v_mov_b32_e32 v62, v109
	v_mov_b32_e32 v128, v121
	v_mov_b32_e32 v72, v39
	ds_read_b128 v[36:39], v79 offset:32
	v_mov_b32_e32 v168, v112
	v_mov_b32_e32 v169, v116
	v_mov_b32_e32 v116, v113
	v_mov_b32_e32 v170, v124
	s_waitcnt lgkmcnt(1)
	v_mov_b32_e32 v171, v132
	v_mov_b32_e32 v132, v125
	s_or_b32 s5, s92, s63
	s_waitcnt vmcnt(34)
	v_pk_fma_f32 v[66:67], v[66:67], v[134:135], v[8:9] op_sel_hi:[1,0,1]
	v_pk_fma_f32 v[106:107], v[162:163], v[134:135], v[6:7] op_sel_hi:[1,0,1]
	v_pk_fma_f32 v[90:91], v[90:91], v[134:135], v[4:5] op_sel_hi:[1,0,1]
	v_pk_fma_f32 v[92:93], v[92:93], v[134:135], v[2:3] op_sel_hi:[1,0,1]
	s_waitcnt vmcnt(33)
	v_pk_fma_f32 v[66:67], v[70:71], v[136:137], v[66:67] op_sel_hi:[1,0,1]
	v_pk_fma_f32 v[70:71], v[98:99], v[136:137], v[106:107] op_sel_hi:[1,0,1]
	v_pk_fma_f32 v[60:61], v[60:61], v[136:137], v[90:91] op_sel_hi:[1,0,1]
	v_pk_fma_f32 v[98:99], v[126:127], v[136:137], v[92:93] op_sel_hi:[1,0,1]
	s_waitcnt vmcnt(32)
	v_pk_fma_f32 v[60:61], v[166:167], v[138:139], v[60:61] op_sel_hi:[1,0,1]
	v_pk_fma_f32 v[126:127], v[118:119], v[138:139], v[98:99] op_sel_hi:[1,0,1]
	v_pk_fma_f32 v[66:67], v[74:75], v[138:139], v[66:67] op_sel_hi:[1,0,1]
	s_waitcnt vmcnt(31)
	v_pk_fma_f32 v[134:135], v[62:63], v[140:141], v[60:61] op_sel_hi:[1,0,1]
	v_pk_fma_f32 v[136:137], v[128:129], v[140:141], v[126:127] op_sel_hi:[1,0,1]
	v_mov_b32_e32 v166, v110
	v_mov_b32_e32 v167, v114
	v_mov_b32_e32 v114, v111
	v_mov_b32_e32 v110, v122
	v_mov_b32_e32 v111, v130
	ds_read_b128 v[2:5], v79 offset:8224
	ds_read_b128 v[90:93], v79 offset:8240
	v_pk_fma_f32 v[74:75], v[164:165], v[138:139], v[70:71] op_sel_hi:[1,0,1]
	ds_read_b128 v[106:109], v79 offset:16416
	ds_read_b128 v[118:121], v79 offset:16432
	v_pk_fma_f32 v[66:67], v[72:73], v[140:141], v[66:67] op_sel_hi:[1,0,1]
	ds_read_b128 v[70:73], v79 offset:24608
	ds_read_b128 v[60:63], v79 offset:32800
	ds_read_b128 v[126:129], v79 offset:40992
	v_mov_b32_e32 v130, v123
	s_waitcnt vmcnt(30)
	v_pk_fma_f32 v[122:123], v[166:167], v[142:143], v[134:135] op_sel_hi:[1,0,1]
	v_pk_fma_f32 v[124:125], v[110:111], v[142:143], v[136:137] op_sel_hi:[1,0,1]
	ds_read_b128 v[110:113], v79 offset:49184
	ds_read_b128 v[134:137], v79 offset:57376
	v_pk_fma_f32 v[74:75], v[100:101], v[140:141], v[74:75] op_sel_hi:[1,0,1]
	v_mov_b32_e32 v138, v50
	v_mov_b32_e32 v139, v86
	v_mov_b32_e32 v162, v94
	v_mov_b32_e32 v163, v102
	v_mov_b32_e32 v86, v51
	v_mov_b32_e32 v102, v95
	v_pk_fma_f32 v[66:67], v[138:139], v[142:143], v[66:67] op_sel_hi:[1,0,1]
	v_pk_fma_f32 v[74:75], v[162:163], v[142:143], v[74:75] op_sel_hi:[1,0,1]
	v_mov_b32_e32 v140, v52
	v_mov_b32_e32 v141, v88
	v_mov_b32_e32 v164, v96
	v_mov_b32_e32 v165, v104
	s_waitcnt vmcnt(29)
	v_pk_fma_f32 v[66:67], v[86:87], v[144:145], v[66:67] op_sel_hi:[1,0,1]
	v_pk_fma_f32 v[74:75], v[102:103], v[144:145], v[74:75] op_sel_hi:[1,0,1]
	v_pk_fma_f32 v[86:87], v[114:115], v[144:145], v[122:123] op_sel_hi:[1,0,1]
	v_pk_fma_f32 v[102:103], v[130:131], v[144:145], v[124:125] op_sel_hi:[1,0,1]
	ds_read_b128 v[6:9], v79 offset:48
	ds_read_b128 v[98:101], v79 offset:24624
	v_mov_b32_e32 v88, v53
	v_mov_b32_e32 v104, v97
	ds_read_b128 v[50:53], v79 offset:32816
	ds_read_b128 v[94:97], v79 offset:41008
	ds_read_b128 v[122:125], v79 offset:49200
	s_waitcnt vmcnt(28)
	v_pk_fma_f32 v[66:67], v[140:141], v[146:147], v[66:67] op_sel_hi:[1,0,1]
	v_pk_fma_f32 v[74:75], v[164:165], v[146:147], v[74:75] op_sel_hi:[1,0,1]
	v_pk_fma_f32 v[114:115], v[168:169], v[146:147], v[86:87] op_sel_hi:[1,0,1]
	v_pk_fma_f32 v[130:131], v[170:171], v[146:147], v[102:103] op_sel_hi:[1,0,1]
	ds_read_b128 v[138:141], v79 offset:57392
	s_waitcnt vmcnt(27)
	v_pk_fma_f32 v[66:67], v[88:89], v[148:149], v[66:67] op_sel_hi:[1,0,1]
	v_pk_fma_f32 v[74:75], v[104:105], v[148:149], v[74:75] op_sel_hi:[1,0,1]
	v_pk_fma_f32 v[142:143], v[116:117], v[148:149], v[114:115] op_sel_hi:[1,0,1]
	v_pk_fma_f32 v[144:145], v[132:133], v[148:149], v[130:131] op_sel_hi:[1,0,1]
	s_waitcnt lgkmcnt(14)
	v_mov_b32_e32 v146, v36
	v_mov_b32_e32 v147, v2
	s_waitcnt lgkmcnt(12)
	v_mov_b32_e32 v162, v106
	s_waitcnt lgkmcnt(10)
	v_mov_b32_e32 v163, v70
	v_mov_b32_e32 v70, v107
	v_mov_b32_e32 v164, v108
	v_mov_b32_e32 v165, v72
	v_mov_b32_e32 v72, v109
	s_waitcnt lgkmcnt(9)
	v_mov_b32_e32 v106, v60
	s_waitcnt lgkmcnt(8)
	v_mov_b32_e32 v107, v126
	s_waitcnt lgkmcnt(7)
	v_mov_b32_e32 v108, v110
	s_waitcnt lgkmcnt(6)
	v_mov_b32_e32 v109, v134
	v_mov_b32_e32 v2, v37
	v_mov_b32_e32 v126, v61
	v_mov_b32_e32 v134, v111
	v_mov_b32_e32 v168, v112
	v_mov_b32_e32 v169, v136
	v_mov_b32_e32 v136, v113
	s_waitcnt vmcnt(26)
	v_pk_fma_f32 v[66:67], v[146:147], v[150:151], v[66:67] op_sel_hi:[1,0,1]
	v_pk_fma_f32 v[74:75], v[162:163], v[150:151], v[74:75] op_sel_hi:[1,0,1]
	v_pk_fma_f32 v[110:111], v[106:107], v[150:151], v[142:143] op_sel_hi:[1,0,1]
	v_pk_fma_f32 v[112:113], v[108:109], v[150:151], v[144:145] op_sel_hi:[1,0,1]
	v_mov_b32_e32 v148, v38
	v_mov_b32_e32 v149, v4
	v_mov_b32_e32 v166, v62
	v_mov_b32_e32 v167, v128
	s_waitcnt vmcnt(25)
	v_pk_fma_f32 v[2:3], v[2:3], v[152:153], v[66:67] op_sel_hi:[1,0,1]
	v_pk_fma_f32 v[66:67], v[70:71], v[152:153], v[74:75] op_sel_hi:[1,0,1]
	v_pk_fma_f32 v[70:71], v[126:127], v[152:153], v[110:111] op_sel_hi:[1,0,1]
	v_pk_fma_f32 v[74:75], v[134:135], v[152:153], v[112:113] op_sel_hi:[1,0,1]
	ds_read_b128 v[86:89], v79 offset:64
	ds_read_b128 v[102:105], v79 offset:80
	ds_read_b128 v[114:117], v79 offset:8256
	ds_read_b128 v[130:133], v79 offset:8272
	v_mov_b32_e32 v4, v39
	v_mov_b32_e32 v128, v63
	s_waitcnt vmcnt(24)
	v_pk_fma_f32 v[2:3], v[148:149], v[154:155], v[2:3] op_sel_hi:[1,0,1]
	v_pk_fma_f32 v[66:67], v[164:165], v[154:155], v[66:67] op_sel_hi:[1,0,1]
	v_pk_fma_f32 v[126:127], v[166:167], v[154:155], v[70:71] op_sel_hi:[1,0,1]
	v_pk_fma_f32 v[74:75], v[168:169], v[154:155], v[74:75] op_sel_hi:[1,0,1]
	ds_read_b128 v[36:39], v79 offset:16448
	ds_read_b128 v[60:63], v79 offset:16464
	ds_read_b128 v[106:109], v79 offset:24640
	ds_read_b128 v[110:113], v79 offset:24656
	ds_read_b128 v[142:145], v79 offset:32832
	ds_read_b128 v[146:149], v79 offset:41024
	s_waitcnt vmcnt(23)
	v_pk_fma_f32 v[150:151], v[4:5], v[32:33], v[2:3] op_sel_hi:[1,0,1]
	v_pk_fma_f32 v[66:67], v[72:73], v[32:33], v[66:67] op_sel_hi:[1,0,1]
	v_pk_fma_f32 v[152:153], v[128:129], v[32:33], v[126:127] op_sel_hi:[1,0,1]
	ds_read_b128 v[126:129], v79 offset:49216
	v_pk_fma_f32 v[32:33], v[136:137], v[32:33], v[74:75] op_sel_hi:[1,0,1]
	s_waitcnt lgkmcnt(14)
	v_mov_b32_e32 v74, v6
	v_mov_b32_e32 v75, v90
	v_mov_b32_e32 v90, v7
	v_mov_b32_e32 v154, v8
	v_mov_b32_e32 v155, v92
	v_mov_b32_e32 v92, v9
	v_mov_b32_e32 v162, v118
	v_mov_b32_e32 v163, v98
	v_mov_b32_e32 v98, v119
	v_mov_b32_e32 v164, v120
	v_mov_b32_e32 v165, v100
	v_mov_b32_e32 v100, v121
	v_mov_b32_e32 v118, v50
	s_waitcnt lgkmcnt(13)
	v_mov_b32_e32 v119, v94
	s_waitcnt lgkmcnt(12)
	v_mov_b32_e32 v120, v122
	s_waitcnt lgkmcnt(11)
	v_mov_b32_e32 v121, v138
	ds_read_b128 v[6:9], v79 offset:57408
	v_mov_b32_e32 v94, v51
	v_mov_b32_e32 v138, v123
	s_waitcnt vmcnt(22)
	v_pk_fma_f32 v[74:75], v[74:75], v[156:157], v[150:151] op_sel_hi:[1,0,1]
	v_pk_fma_f32 v[66:67], v[162:163], v[156:157], v[66:67] op_sel_hi:[1,0,1]
	v_pk_fma_f32 v[122:123], v[118:119], v[156:157], v[152:153] op_sel_hi:[1,0,1]
	v_pk_fma_f32 v[32:33], v[120:121], v[156:157], v[32:33] op_sel_hi:[1,0,1]
	v_mov_b32_e32 v166, v52
	v_mov_b32_e32 v167, v96
	v_mov_b32_e32 v168, v124
	v_mov_b32_e32 v169, v140
	s_waitcnt vmcnt(21)
	v_pk_fma_f32 v[74:75], v[90:91], v[158:159], v[74:75] op_sel_hi:[1,0,1]
	v_pk_fma_f32 v[66:67], v[98:99], v[158:159], v[66:67] op_sel_hi:[1,0,1]
	v_pk_fma_f32 v[90:91], v[94:95], v[158:159], v[122:123] op_sel_hi:[1,0,1]
	v_pk_fma_f32 v[32:33], v[138:139], v[158:159], v[32:33] op_sel_hi:[1,0,1]
	v_mov_b32_e32 v96, v53
	v_mov_b32_e32 v140, v125
	s_waitcnt vmcnt(20)
	v_pk_fma_f32 v[74:75], v[154:155], v[160:161], v[74:75] op_sel_hi:[1,0,1]
	v_pk_fma_f32 v[66:67], v[164:165], v[160:161], v[66:67] op_sel_hi:[1,0,1]
	v_pk_fma_f32 v[94:95], v[166:167], v[160:161], v[90:91] op_sel_hi:[1,0,1]
	v_pk_fma_f32 v[32:33], v[168:169], v[160:161], v[32:33] op_sel_hi:[1,0,1]
	ds_read_b128 v[2:5], v79 offset:32848
	ds_read_b128 v[70:73], v79 offset:41040
	ds_read_b128 v[134:137], v79 offset:49232
	ds_read_b128 v[50:53], v79 offset:57424
	s_waitcnt vmcnt(19)
	v_pk_fma_f32 v[74:75], v[92:93], v[42:43], v[74:75] op_sel_hi:[1,0,1]
	v_pk_fma_f32 v[66:67], v[100:101], v[42:43], v[66:67] op_sel_hi:[1,0,1]
	v_pk_fma_f32 v[158:159], v[96:97], v[42:43], v[94:95] op_sel_hi:[1,0,1]
	v_pk_fma_f32 v[32:33], v[140:141], v[42:43], v[32:33] op_sel_hi:[1,0,1]
	s_waitcnt lgkmcnt(14)
	v_mov_b32_e32 v42, v86
	s_waitcnt lgkmcnt(13)
	v_mov_b32_e32 v43, v114
	v_mov_b32_e32 v114, v87
	s_waitcnt lgkmcnt(11)
	v_mov_b32_e32 v86, v36
	s_waitcnt lgkmcnt(9)
	v_mov_b32_e32 v87, v106
	s_waitcnt lgkmcnt(7)
	v_mov_b32_e32 v164, v142
	s_waitcnt lgkmcnt(6)
	v_mov_b32_e32 v165, v146
	v_mov_b32_e32 v146, v143
	v_mov_b32_e32 v142, v144
	v_mov_b32_e32 v143, v148
	v_mov_b32_e32 v148, v145
	s_waitcnt lgkmcnt(5)
	v_mov_b32_e32 v144, v126
	s_waitcnt lgkmcnt(4)
	v_mov_b32_e32 v145, v6
	s_waitcnt vmcnt(18)
	v_pk_fma_f32 v[42:43], v[42:43], v[24:25], v[74:75] op_sel_hi:[1,0,1]
	v_mov_b32_e32 v160, v88
	v_mov_b32_e32 v161, v116
	v_mov_b32_e32 v106, v37
	v_mov_b32_e32 v6, v127
	v_pk_fma_f32 v[66:67], v[86:87], v[24:25], v[66:67] op_sel_hi:[1,0,1]
	v_pk_fma_f32 v[74:75], v[164:165], v[24:25], v[158:159] op_sel_hi:[1,0,1]
	v_pk_fma_f32 v[24:25], v[144:145], v[24:25], v[32:33] op_sel_hi:[1,0,1]
	s_waitcnt vmcnt(17)
	v_pk_fma_f32 v[32:33], v[114:115], v[20:21], v[42:43] op_sel_hi:[1,0,1]
	v_mov_b32_e32 v116, v89
	v_mov_b32_e32 v162, v38
	v_mov_b32_e32 v163, v108
	v_mov_b32_e32 v166, v128
	v_mov_b32_e32 v167, v8
	v_pk_fma_f32 v[42:43], v[106:107], v[20:21], v[66:67] op_sel_hi:[1,0,1]
	v_pk_fma_f32 v[66:67], v[146:147], v[20:21], v[74:75] op_sel_hi:[1,0,1]
	v_pk_fma_f32 v[6:7], v[6:7], v[20:21], v[24:25] op_sel_hi:[1,0,1]
	s_waitcnt vmcnt(16)
	v_pk_fma_f32 v[20:21], v[160:161], v[18:19], v[32:33] op_sel_hi:[1,0,1]
	ds_read_b128 v[118:121], v79 offset:96
	ds_read_b128 v[122:125], v79 offset:112
	ds_read_b128 v[150:153], v79 offset:8288
	ds_read_b128 v[154:157], v79 offset:8304
	ds_read_b128 v[90:93], v79 offset:16480
	ds_read_b128 v[98:101], v79 offset:16496
	ds_read_b128 v[94:97], v79 offset:24672
	ds_read_b128 v[138:141], v79 offset:24688
	v_mov_b32_e32 v108, v39
	v_mov_b32_e32 v8, v129
	ds_read_b128 v[36:39], v79 offset:32864
	ds_read_b128 v[126:129], v79 offset:32880
	ds_read_b128 v[86:89], v79 offset:41056
	ds_read_b128 v[144:147], v79 offset:41072
	v_pk_fma_f32 v[24:25], v[162:163], v[18:19], v[42:43] op_sel_hi:[1,0,1]
	ds_read_b128 v[158:161], v79 offset:49248
	ds_read_b128 v[162:165], v79 offset:49264
	v_pk_fma_f32 v[32:33], v[142:143], v[18:19], v[66:67] op_sel_hi:[1,0,1]
	v_pk_fma_f32 v[6:7], v[166:167], v[18:19], v[6:7] op_sel_hi:[1,0,1]
	s_waitcnt vmcnt(15)
	v_pk_fma_f32 v[18:19], v[116:117], v[16:17], v[20:21] op_sel_hi:[1,0,1]
	ds_read_b128 v[114:117], v79 offset:57440
	v_pk_fma_f32 v[20:21], v[108:109], v[16:17], v[24:25] op_sel_hi:[1,0,1]
	v_pk_fma_f32 v[24:25], v[148:149], v[16:17], v[32:33] op_sel_hi:[1,0,1]
	v_pk_fma_f32 v[16:17], v[8:9], v[16:17], v[6:7] op_sel_hi:[1,0,1]
	v_mov_b32_e32 v6, v102
	v_mov_b32_e32 v7, v130
	v_mov_b32_e32 v8, v60
	v_mov_b32_e32 v9, v110
	v_mov_b32_e32 v110, v61
	s_waitcnt lgkmcnt(14)
	v_mov_b32_e32 v60, v2
	v_mov_b32_e32 v61, v70
	v_mov_b32_e32 v66, v134
	v_mov_b32_e32 v67, v50
	v_mov_b32_e32 v130, v103
	v_mov_b32_e32 v70, v3
	v_mov_b32_e32 v50, v135
	s_waitcnt vmcnt(14)
	v_pk_fma_f32 v[18:19], v[6:7], v[14:15], v[18:19] op_sel_hi:[1,0,1]
	v_pk_fma_f32 v[20:21], v[8:9], v[14:15], v[20:21] op_sel_hi:[1,0,1]
	v_pk_fma_f32 v[24:25], v[60:61], v[14:15], v[24:25] op_sel_hi:[1,0,1]
	v_pk_fma_f32 v[14:15], v[66:67], v[14:15], v[16:17] op_sel_hi:[1,0,1]
	v_mad_i64_i32 v[48:49], s[4:5], s5, v1, v[82:83]
	v_mov_b32_e32 v32, v104
	v_mov_b32_e32 v33, v132
	v_mov_b32_e32 v42, v62
	v_mov_b32_e32 v43, v112
	v_mov_b32_e32 v112, v63
	v_mov_b32_e32 v62, v4
	v_mov_b32_e32 v63, v72
	v_mov_b32_e32 v74, v136
	v_mov_b32_e32 v75, v52
	s_waitcnt vmcnt(13)
	v_pk_fma_f32 v[16:17], v[130:131], v[12:13], v[18:19] op_sel_hi:[1,0,1]
	v_pk_fma_f32 v[18:19], v[110:111], v[12:13], v[20:21] op_sel_hi:[1,0,1]
	v_pk_fma_f32 v[20:21], v[70:71], v[12:13], v[24:25] op_sel_hi:[1,0,1]
	v_pk_fma_f32 v[12:13], v[50:51], v[12:13], v[14:15] op_sel_hi:[1,0,1]
	ds_read_b128 v[106:109], v79 offset:57456
	v_mov_b32_e32 v132, v105
	v_mov_b32_e32 v72, v5
	v_mov_b32_e32 v52, v137
	s_waitcnt vmcnt(12)
	v_pk_fma_f32 v[24:25], v[32:33], v[10:11], v[16:17] op_sel_hi:[1,0,1]
	v_pk_fma_f32 v[32:33], v[42:43], v[10:11], v[18:19] op_sel_hi:[1,0,1]
	v_pk_fma_f32 v[42:43], v[62:63], v[10:11], v[20:21] op_sel_hi:[1,0,1]
	v_pk_fma_f32 v[50:51], v[74:75], v[10:11], v[12:13] op_sel_hi:[1,0,1]
	global_load_dword v48, v[48:49], off nt
	s_waitcnt vmcnt(12)
	v_pk_fma_f32 v[60:61], v[132:133], v[22:23], v[24:25] op_sel_hi:[1,0,1]
	v_pk_fma_f32 v[32:33], v[112:113], v[22:23], v[32:33] op_sel_hi:[1,0,1]
	v_pk_fma_f32 v[42:43], v[72:73], v[22:23], v[42:43] op_sel_hi:[1,0,1]
	v_pk_fma_f32 v[50:51], v[52:53], v[22:23], v[50:51] op_sel_hi:[1,0,1]
	v_mov_b32_e32 v52, v118
	s_waitcnt lgkmcnt(13)
	v_mov_b32_e32 v53, v150
	s_waitcnt lgkmcnt(11)
	v_mov_b32_e32 v66, v90
	s_waitcnt lgkmcnt(9)
	v_mov_b32_e32 v67, v94
	s_waitcnt lgkmcnt(7)
	v_mov_b32_e32 v72, v36
	s_waitcnt lgkmcnt(5)
	v_mov_b32_e32 v73, v86
	v_mov_b32_e32 v86, v37
	s_waitcnt lgkmcnt(3)
	v_mov_b32_e32 v36, v158
	s_waitcnt lgkmcnt(1)
	v_mov_b32_e32 v37, v114
	v_mov_b32_e32 v150, v119
	v_mov_b32_e32 v94, v91
	v_mov_b32_e32 v74, v38
	v_mov_b32_e32 v75, v88
	v_mov_b32_e32 v88, v39
	v_mov_b32_e32 v114, v159
	s_waitcnt vmcnt(11)
	v_pk_fma_f32 v[38:39], v[52:53], v[30:31], v[60:61] op_sel_hi:[1,0,1]
	v_pk_fma_f32 v[52:53], v[66:67], v[30:31], v[32:33] op_sel_hi:[1,0,1]
	v_pk_fma_f32 v[42:43], v[72:73], v[30:31], v[42:43] op_sel_hi:[1,0,1]
	v_pk_fma_f32 v[36:37], v[36:37], v[30:31], v[50:51] op_sel_hi:[1,0,1]
	v_mov_b32_e32 v62, v120
	v_mov_b32_e32 v63, v152
	v_mov_b32_e32 v70, v92
	v_mov_b32_e32 v71, v96
	v_mov_b32_e32 v110, v160
	v_mov_b32_e32 v111, v116
	s_waitcnt vmcnt(10)
	v_pk_fma_f32 v[50:51], v[150:151], v[28:29], v[38:39] op_sel_hi:[1,0,1]
	v_pk_fma_f32 v[52:53], v[94:95], v[28:29], v[52:53] op_sel_hi:[1,0,1]
	v_pk_fma_f32 v[42:43], v[86:87], v[28:29], v[42:43] op_sel_hi:[1,0,1]
	v_pk_fma_f32 v[28:29], v[114:115], v[28:29], v[36:37] op_sel_hi:[1,0,1]
	ds_read_b128 v[166:169], v79 offset:128
	ds_read_b128 v[170:173], v79 offset:144
	ds_read_b128 v[2:5], v79 offset:8320
	ds_read_b128 v[6:9], v79 offset:8336
	ds_read_b128 v[102:105], v79 offset:16512
	ds_read_b128 v[174:177], v79 offset:16528
	ds_read_b128 v[14:17], v79 offset:24704
	ds_read_b128 v[18:21], v79 offset:24720
	ds_read_b128 v[178:181], v79 offset:32896
	ds_read_b128 v[182:185], v79 offset:32912
	ds_read_b128 v[10:13], v79 offset:41088
	ds_read_b128 v[22:25], v79 offset:41104
	v_mov_b32_e32 v152, v121
	v_mov_b32_e32 v96, v93
	v_mov_b32_e32 v116, v161
	ds_read_b128 v[90:93], v79 offset:49280
	ds_read_b128 v[158:161], v79 offset:49296
	ds_read_b128 v[30:33], v79 offset:57472
	ds_read_b128 v[36:39], v79 offset:57488
	s_waitcnt vmcnt(9)
	v_pk_fma_f32 v[50:51], v[62:63], v[26:27], v[50:51] op_sel_hi:[1,0,1]
	v_pk_fma_f32 v[52:53], v[70:71], v[26:27], v[52:53] op_sel_hi:[1,0,1]
	v_pk_fma_f32 v[42:43], v[74:75], v[26:27], v[42:43] op_sel_hi:[1,0,1]
	v_pk_fma_f32 v[60:61], v[110:111], v[26:27], v[28:29] op_sel_hi:[1,0,1]
	s_waitcnt vmcnt(8)
	v_pk_fma_f32 v[62:63], v[152:153], v[40:41], v[50:51] op_sel_hi:[1,0,1]
	v_pk_fma_f32 v[66:67], v[96:97], v[40:41], v[52:53] op_sel_hi:[1,0,1]
	v_pk_fma_f32 v[70:71], v[88:89], v[40:41], v[42:43] op_sel_hi:[1,0,1]
	v_pk_fma_f32 v[72:73], v[116:117], v[40:41], v[60:61] op_sel_hi:[1,0,1]
	v_mov_b32_e32 v60, v122
	v_mov_b32_e32 v61, v154
	v_mov_b32_e32 v86, v98
	v_mov_b32_e32 v87, v138
	v_mov_b32_e32 v138, v99
	v_mov_b32_e32 v98, v126
	v_mov_b32_e32 v99, v144
	v_mov_b32_e32 v110, v162
	s_waitcnt lgkmcnt(14)
	v_mov_b32_e32 v111, v106
	v_mov_b32_e32 v154, v123
	v_mov_b32_e32 v144, v127
	v_mov_b32_e32 v106, v163
	s_waitcnt vmcnt(7)
	v_pk_fma_f32 v[114:115], v[60:61], v[46:47], v[62:63] op_sel_hi:[1,0,1]
	v_pk_fma_f32 v[66:67], v[86:87], v[46:47], v[66:67] op_sel_hi:[1,0,1]
	v_pk_fma_f32 v[70:71], v[98:99], v[46:47], v[70:71] op_sel_hi:[1,0,1]
	v_pk_fma_f32 v[46:47], v[110:111], v[46:47], v[72:73] op_sel_hi:[1,0,1]
	ds_read_b128 v[186:189], v79 offset:160
	ds_read_b128 v[190:193], v79 offset:176
	v_mov_b32_e32 v74, v124
	v_mov_b32_e32 v75, v156
	v_mov_b32_e32 v88, v100
	v_mov_b32_e32 v89, v140
	v_mov_b32_e32 v140, v101
	v_mov_b32_e32 v100, v128
	v_mov_b32_e32 v101, v146
	v_mov_b32_e32 v112, v164
	v_mov_b32_e32 v113, v108
	v_mov_b32_e32 v108, v165
	ds_read_b128 v[162:165], v79 offset:32928
	ds_read_b128 v[198:201], v79 offset:32944
	s_waitcnt vmcnt(6)
	v_pk_fma_f32 v[72:73], v[154:155], v[44:45], v[114:115] op_sel_hi:[1,0,1]
	v_pk_fma_f32 v[66:67], v[138:139], v[44:45], v[66:67] op_sel_hi:[1,0,1]
	v_pk_fma_f32 v[70:71], v[144:145], v[44:45], v[70:71] op_sel_hi:[1,0,1]
	v_pk_fma_f32 v[86:87], v[106:107], v[44:45], v[46:47] op_sel_hi:[1,0,1]
	v_mov_b32_e32 v156, v125
	v_mov_b32_e32 v146, v129
	s_waitcnt vmcnt(5)
	v_pk_fma_f32 v[72:73], v[74:75], v[64:65], v[72:73] op_sel_hi:[1,0,1]
	v_pk_fma_f32 v[74:75], v[88:89], v[64:65], v[66:67] op_sel_hi:[1,0,1]
	v_pk_fma_f32 v[70:71], v[100:101], v[64:65], v[70:71] op_sel_hi:[1,0,1]
	v_pk_fma_f32 v[86:87], v[112:113], v[64:65], v[86:87] op_sel_hi:[1,0,1]
	s_waitcnt vmcnt(4)
	v_pk_fma_f32 v[148:149], v[156:157], v[68:69], v[72:73] op_sel_hi:[1,0,1]
	v_pk_fma_f32 v[144:145], v[140:141], v[68:69], v[74:75] op_sel_hi:[1,0,1]
	v_pk_fma_f32 v[138:139], v[146:147], v[68:69], v[70:71] op_sel_hi:[1,0,1]
	v_pk_fma_f32 v[140:141], v[108:109], v[68:69], v[86:87] op_sel_hi:[1,0,1]
	v_mov_b32_e32 v154, v166
	s_waitcnt lgkmcnt(14)
	v_mov_b32_e32 v155, v2
	v_mov_b32_e32 v152, v102
	s_waitcnt lgkmcnt(13)
	v_mov_b32_e32 v153, v14
	s_waitcnt lgkmcnt(11)
	v_mov_b32_e32 v150, v178
	s_waitcnt lgkmcnt(9)
	v_mov_b32_e32 v151, v10
	s_waitcnt lgkmcnt(7)
	v_mov_b32_e32 v156, v90
	s_waitcnt lgkmcnt(5)
	v_mov_b32_e32 v157, v30
	s_or_b32 s6, s92, s64
	s_or_b32 s8, s92, s65
	s_or_b32 s94, s92, s66
	s_or_b32 s1, s92, s67
	v_mov_b32_e32 v2, v167
	v_mov_b32_e32 v14, v103
	v_mov_b32_e32 v10, v179
	v_mov_b32_e32 v30, v91
	s_waitcnt vmcnt(3)
	v_pk_fma_f32 v[148:149], v[154:155], v[58:59], v[148:149] op_sel_hi:[1,0,1]
	v_pk_fma_f32 v[144:145], v[152:153], v[58:59], v[144:145] op_sel_hi:[1,0,1]
	v_pk_fma_f32 v[138:139], v[150:151], v[58:59], v[138:139] op_sel_hi:[1,0,1]
	v_pk_fma_f32 v[58:59], v[156:157], v[58:59], v[140:141] op_sel_hi:[1,0,1]
	s_or_b32 s3, s92, s68
	s_or_b32 s15, s92, s69
	s_or_b32 s14, s92, s70
	s_or_b32 s33, s92, s71
	s_or_b32 s37, s92, s72
	s_or_b32 s34, s92, s73
	s_or_b32 s36, s92, s74
	s_or_b32 s38, s92, s75
	v_mad_i64_i32 v[34:35], s[4:5], s6, v1, v[82:83]
	v_mad_i64_i32 v[84:85], s[4:5], s8, v1, v[82:83]
	v_mov_b32_e32 v132, v168
	v_mov_b32_e32 v133, v4
	v_mov_b32_e32 v136, v104
	v_mov_b32_e32 v137, v16
	v_mov_b32_e32 v142, v180
	v_mov_b32_e32 v143, v12
	v_mov_b32_e32 v146, v92
	v_mov_b32_e32 v147, v32
	v_mov_b32_e32 v134, v158
	s_waitcnt lgkmcnt(4)
	v_mov_b32_e32 v135, v36
	v_mov_b32_e32 v36, v159
	v_mov_b32_e32 v122, v160
	v_mov_b32_e32 v123, v38
	v_mov_b32_e32 v38, v161
	v_mad_i64_i32 v[158:159], s[4:5], s94, v1, v[82:83]
	v_mad_i64_i32 v[160:161], s[4:5], s1, v1, v[82:83]
	s_waitcnt vmcnt(2)
	v_pk_fma_f32 v[2:3], v[2:3], v[56:57], v[148:149] op_sel_hi:[1,0,1]
	v_pk_fma_f32 v[14:15], v[14:15], v[56:57], v[144:145] op_sel_hi:[1,0,1]
	v_pk_fma_f32 v[10:11], v[10:11], v[56:57], v[138:139] op_sel_hi:[1,0,1]
	v_pk_fma_f32 v[30:31], v[30:31], v[56:57], v[58:59] op_sel_hi:[1,0,1]
	ds_read_b128 v[26:29], v79 offset:8352
	ds_read_b128 v[50:53], v79 offset:8368
	ds_read_b128 v[94:97], v79 offset:16544
	ds_read_b128 v[194:197], v79 offset:16560
	ds_read_b128 v[40:43], v79 offset:24736
	ds_read_b128 v[60:63], v79 offset:24752
	ds_read_b128 v[44:47], v79 offset:41120
	ds_read_b128 v[64:67], v79 offset:41136
	ds_read_b128 v[202:205], v79 offset:49312
	ds_read_b128 v[206:209], v79 offset:49328
	ds_read_b128 v[72:75], v79 offset:57504
	ds_read_b128 v[68:71], v79 offset:57520
	v_mov_b32_e32 v108, v170
	s_waitcnt lgkmcnt(14)
	v_mov_b32_e32 v102, v186
	v_mov_b32_e32 v88, v188
	s_waitcnt lgkmcnt(13)
	v_mov_b32_e32 v124, v162
	v_mov_b32_e32 v104, v164
	v_mad_i64_i32 v[154:155], s[4:5], s3, v1, v[82:83]
	v_mad_i64_i32 v[152:153], s[4:5], s15, v1, v[82:83]
	v_mad_i64_i32 v[150:151], s[6:7], s14, v1, v[82:83]
	v_mad_i64_i32 v[140:141], s[6:7], s33, v1, v[82:83]
	v_mad_i64_i32 v[156:157], s[6:7], s37, v1, v[82:83]
	v_mad_i64_i32 v[56:57], s[6:7], s34, v1, v[82:83]
	s_waitcnt vmcnt(1)
	v_pk_fma_f32 v[2:3], v[132:133], v[54:55], v[2:3] op_sel_hi:[1,0,1]
	v_mad_i64_i32 v[58:59], s[6:7], s36, v1, v[82:83]
	v_pk_fma_f32 v[14:15], v[136:137], v[54:55], v[14:15] op_sel_hi:[1,0,1]
	v_mad_i64_i32 v[132:133], s[6:7], s38, v1, v[82:83]
	v_pk_fma_f32 v[10:11], v[142:143], v[54:55], v[10:11] op_sel_hi:[1,0,1]
	v_pk_fma_f32 v[30:31], v[146:147], v[54:55], v[30:31] op_sel_hi:[1,0,1]
	global_load_dword v34, v[34:35], off nt
	s_nop 0
	global_load_dword v54, v[84:85], off nt
	s_nop 0
	global_load_dword v84, v[158:159], off nt
	s_nop 0
	global_load_dword v158, v[160:161], off nt
	s_nop 0
	global_load_dword v160, v[154:155], off nt
	global_load_dword v162, v[152:153], off nt
	global_load_dword v164, v[150:151], off nt
	global_load_dword v166, v[140:141], off nt
	global_load_dword v168, v[156:157], off nt
	global_load_dword v170, v[56:57], off nt
	global_load_dword v186, v[58:59], off nt
	global_load_dword v188, v[132:133], off nt
	v_mov_b32_e32 v4, v169
	v_mov_b32_e32 v16, v105
	v_mov_b32_e32 v12, v181
	v_mov_b32_e32 v32, v93
	v_mov_b32_e32 v109, v6
	v_mov_b32_e32 v118, v174
	v_mov_b32_e32 v119, v18
	v_mov_b32_e32 v128, v182
	v_mov_b32_e32 v129, v22
	s_waitcnt vmcnt(12)
	v_pk_fma_f32 v[2:3], v[4:5], v[48:49], v[2:3] op_sel_hi:[1,0,1]
	v_pk_fma_f32 v[4:5], v[16:17], v[48:49], v[14:15] op_sel_hi:[1,0,1]
	v_pk_fma_f32 v[10:11], v[12:13], v[48:49], v[10:11] op_sel_hi:[1,0,1]
	v_pk_fma_f32 v[12:13], v[32:33], v[48:49], v[30:31] op_sel_hi:[1,0,1]
	v_mov_b32_e32 v6, v171
	v_mov_b32_e32 v18, v175
	v_mov_b32_e32 v22, v183
	v_mov_b32_e32 v92, v172
	v_mov_b32_e32 v93, v8
	v_mov_b32_e32 v98, v176
	v_mov_b32_e32 v99, v20
	v_mov_b32_e32 v112, v184
	v_mov_b32_e32 v113, v24
	v_mov_b32_e32 v8, v173
	v_mov_b32_e32 v20, v177
	v_mov_b32_e32 v24, v185
	s_waitcnt lgkmcnt(11)
	v_mov_b32_e32 v103, v26
	s_waitcnt lgkmcnt(9)
	v_mov_b32_e32 v114, v94
	s_waitcnt lgkmcnt(7)
	v_mov_b32_e32 v115, v40
	s_waitcnt lgkmcnt(5)
	v_mov_b32_e32 v125, v44
	s_waitcnt lgkmcnt(3)
	v_mov_b32_e32 v130, v202
	s_waitcnt lgkmcnt(1)
	v_mov_b32_e32 v131, v72
	v_mov_b32_e32 v26, v187
	v_mov_b32_e32 v40, v95
	v_mov_b32_e32 v44, v163
	v_mov_b32_e32 v72, v203
	v_mov_b32_e32 v89, v28
	v_mov_b32_e32 v94, v96
	v_mov_b32_e32 v95, v42
	v_mov_b32_e32 v105, v46
	v_mov_b32_e32 v116, v204
	v_mov_b32_e32 v117, v74
	v_mov_b32_e32 v28, v189
	v_mov_b32_e32 v42, v97
	v_mov_b32_e32 v46, v165
	v_mov_b32_e32 v74, v205
	ds_read_b128 v[136:139], v79 offset:192
	ds_read_b128 v[140:143], v79 offset:208
	v_mov_b32_e32 v96, v190
	v_mov_b32_e32 v97, v50
	v_mov_b32_e32 v106, v194
	v_mov_b32_e32 v107, v60
	v_mov_b32_e32 v120, v198
	v_mov_b32_e32 v121, v64
	v_mov_b32_e32 v126, v206
	s_waitcnt lgkmcnt(2)
	v_mov_b32_e32 v127, v68
	v_mov_b32_e32 v50, v191
	v_mov_b32_e32 v60, v195
	v_mov_b32_e32 v64, v199
	v_mov_b32_e32 v68, v207
	s_or_b32 s39, s92, s76
	v_mov_b32_e32 v86, v192
	v_mov_b32_e32 v87, v52
	v_mov_b32_e32 v90, v196
	v_mov_b32_e32 v91, v62
	v_mov_b32_e32 v100, v200
	v_mov_b32_e32 v101, v66
	v_mov_b32_e32 v110, v208
	v_mov_b32_e32 v111, v70
	s_waitcnt vmcnt(11)
	v_pk_fma_f32 v[30:31], v[108:109], v[34:35], v[2:3] op_sel_hi:[1,0,1]
	v_pk_fma_f32 v[32:33], v[118:119], v[34:35], v[4:5] op_sel_hi:[1,0,1]
	v_pk_fma_f32 v[10:11], v[128:129], v[34:35], v[10:11] op_sel_hi:[1,0,1]
	v_pk_fma_f32 v[12:13], v[134:135], v[34:35], v[12:13] op_sel_hi:[1,0,1]
	s_waitcnt vmcnt(10)
	v_pk_fma_f32 v[6:7], v[6:7], v[54:55], v[30:31] op_sel_hi:[1,0,1]
	v_pk_fma_f32 v[18:19], v[18:19], v[54:55], v[32:33] op_sel_hi:[1,0,1]
	v_pk_fma_f32 v[10:11], v[22:23], v[54:55], v[10:11] op_sel_hi:[1,0,1]
	v_pk_fma_f32 v[12:13], v[36:37], v[54:55], v[12:13] op_sel_hi:[1,0,1]
	s_waitcnt vmcnt(9)
	v_pk_fma_f32 v[6:7], v[92:93], v[84:85], v[6:7] op_sel_hi:[1,0,1]
	v_pk_fma_f32 v[18:19], v[98:99], v[84:85], v[18:19] op_sel_hi:[1,0,1]
	v_pk_fma_f32 v[22:23], v[112:113], v[84:85], v[10:11] op_sel_hi:[1,0,1]
	v_pk_fma_f32 v[48:49], v[122:123], v[84:85], v[12:13] op_sel_hi:[1,0,1]
	s_waitcnt vmcnt(8)
	v_pk_fma_f32 v[6:7], v[8:9], v[158:159], v[6:7] op_sel_hi:[1,0,1]
	v_pk_fma_f32 v[8:9], v[20:21], v[158:159], v[18:19] op_sel_hi:[1,0,1]
	v_pk_fma_f32 v[22:23], v[24:25], v[158:159], v[22:23] op_sel_hi:[1,0,1]
	v_pk_fma_f32 v[24:25], v[38:39], v[158:159], v[48:49] op_sel_hi:[1,0,1]
	s_waitcnt vmcnt(7)
	v_pk_fma_f32 v[6:7], v[102:103], v[160:161], v[6:7] op_sel_hi:[1,0,1]
	v_pk_fma_f32 v[8:9], v[114:115], v[160:161], v[8:9] op_sel_hi:[1,0,1]
	v_pk_fma_f32 v[22:23], v[124:125], v[160:161], v[22:23] op_sel_hi:[1,0,1]
	v_pk_fma_f32 v[24:25], v[130:131], v[160:161], v[24:25] op_sel_hi:[1,0,1]
	s_waitcnt vmcnt(6)
	v_pk_fma_f32 v[6:7], v[26:27], v[162:163], v[6:7] op_sel_hi:[1,0,1]
	v_pk_fma_f32 v[8:9], v[40:41], v[162:163], v[8:9] op_sel_hi:[1,0,1]
	v_pk_fma_f32 v[22:23], v[44:45], v[162:163], v[22:23] op_sel_hi:[1,0,1]
	v_pk_fma_f32 v[24:25], v[72:73], v[162:163], v[24:25] op_sel_hi:[1,0,1]
	s_waitcnt vmcnt(5)
	v_pk_fma_f32 v[6:7], v[88:89], v[164:165], v[6:7] op_sel_hi:[1,0,1]
	v_pk_fma_f32 v[8:9], v[94:95], v[164:165], v[8:9] op_sel_hi:[1,0,1]
	v_pk_fma_f32 v[22:23], v[104:105], v[164:165], v[22:23] op_sel_hi:[1,0,1]
	v_pk_fma_f32 v[24:25], v[116:117], v[164:165], v[24:25] op_sel_hi:[1,0,1]
	s_waitcnt vmcnt(4)
	v_pk_fma_f32 v[44:45], v[28:29], v[166:167], v[6:7] op_sel_hi:[1,0,1]
	v_pk_fma_f32 v[42:43], v[42:43], v[166:167], v[8:9] op_sel_hi:[1,0,1]
	v_pk_fma_f32 v[22:23], v[46:47], v[166:167], v[22:23] op_sel_hi:[1,0,1]
	v_pk_fma_f32 v[58:59], v[74:75], v[166:167], v[24:25] op_sel_hi:[1,0,1]
	s_waitcnt vmcnt(3)
	v_pk_fma_f32 v[44:45], v[96:97], v[168:169], v[44:45] op_sel_hi:[1,0,1]
	v_pk_fma_f32 v[42:43], v[106:107], v[168:169], v[42:43] op_sel_hi:[1,0,1]
	v_pk_fma_f32 v[72:73], v[120:121], v[168:169], v[22:23] op_sel_hi:[1,0,1]
	v_pk_fma_f32 v[58:59], v[126:127], v[168:169], v[58:59] op_sel_hi:[1,0,1]
	s_waitcnt vmcnt(2)
	v_pk_fma_f32 v[44:45], v[50:51], v[170:171], v[44:45] op_sel_hi:[1,0,1]
	v_pk_fma_f32 v[42:43], v[60:61], v[170:171], v[42:43] op_sel_hi:[1,0,1]
	v_pk_fma_f32 v[50:51], v[64:65], v[170:171], v[72:73] op_sel_hi:[1,0,1]
	v_pk_fma_f32 v[64:65], v[68:69], v[170:171], v[58:59] op_sel_hi:[1,0,1]
	v_mov_b32_e32 v52, v193
	v_mov_b32_e32 v62, v197
	v_mov_b32_e32 v66, v201
	v_mov_b32_e32 v70, v209
	v_mad_i64_i32 v[172:173], s[6:7], s39, v1, v[82:83]
	s_waitcnt vmcnt(1)
	v_pk_fma_f32 v[68:69], v[86:87], v[186:187], v[44:45] op_sel_hi:[1,0,1]
	v_pk_fma_f32 v[72:73], v[90:91], v[186:187], v[42:43] op_sel_hi:[1,0,1]
	v_pk_fma_f32 v[50:51], v[100:101], v[186:187], v[50:51] op_sel_hi:[1,0,1]
	v_pk_fma_f32 v[74:75], v[110:111], v[186:187], v[64:65] op_sel_hi:[1,0,1]
	s_waitcnt vmcnt(0)
	v_pk_fma_f32 v[186:187], v[52:53], v[188:189], v[68:69] op_sel_hi:[1,0,1]
	v_pk_fma_f32 v[190:191], v[62:63], v[188:189], v[72:73] op_sel_hi:[1,0,1]
	v_pk_fma_f32 v[192:193], v[66:67], v[188:189], v[50:51] op_sel_hi:[1,0,1]
	v_pk_fma_f32 v[188:189], v[70:71], v[188:189], v[74:75] op_sel_hi:[1,0,1]
	s_waitcnt lgkmcnt(0)
	v_mov_b32_e32 v74, v140
	global_load_dword v140, v[172:173], off nt
	ds_read_b128 v[14:17], v79 offset:8384
	ds_read_b128 v[2:5], v79 offset:8400
	ds_read_b128 v[132:135], v79 offset:16576
	ds_read_b128 v[144:147], v79 offset:16592
	ds_read_b128 v[30:33], v79 offset:24768
	ds_read_b128 v[10:13], v79 offset:24784
	ds_read_b128 v[148:151], v79 offset:32960
	ds_read_b128 v[152:155], v79 offset:32976
	ds_read_b128 v[34:37], v79 offset:41152
	ds_read_b128 v[18:21], v79 offset:41168
	ds_read_b128 v[156:159], v79 offset:49344
	ds_read_b128 v[112:115], v79 offset:49360
	ds_read_b128 v[54:57], v79 offset:57536
	ds_read_b128 v[38:41], v79 offset:57552
	s_or_b32 s93, s92, s77
	s_or_b32 s95, s92, s78
	v_mad_i64_i32 v[174:175], s[6:7], s93, v1, v[82:83]
	v_mad_i64_i32 v[176:177], s[6:7], s95, v1, v[82:83]
	v_mov_b32_e32 v194, v136
	s_waitcnt lgkmcnt(13)
	v_mov_b32_e32 v195, v14
	v_mov_b32_e32 v14, v137
	v_mov_b32_e32 v136, v138
	v_mov_b32_e32 v137, v16
	v_mov_b32_e32 v16, v139
	s_waitcnt lgkmcnt(11)
	v_mov_b32_e32 v138, v132
	s_waitcnt lgkmcnt(9)
	v_mov_b32_e32 v139, v30
	v_mov_b32_e32 v30, v133
	v_mov_b32_e32 v66, v134
	v_mov_b32_e32 v67, v32
	v_mov_b32_e32 v32, v135
	s_waitcnt lgkmcnt(7)
	v_mov_b32_e32 v132, v148
	s_waitcnt lgkmcnt(5)
	v_mov_b32_e32 v133, v34
	s_waitcnt lgkmcnt(3)
	v_mov_b32_e32 v134, v156
	s_waitcnt lgkmcnt(1)
	v_mov_b32_e32 v135, v54
	v_mov_b32_e32 v68, v142
	v_mov_b32_e32 v69, v4
	v_mov_b32_e32 v4, v143
	v_mov_b32_e32 v98, v152
	global_load_dword v152, v[176:177], off nt
	ds_read_b128 v[102:105], v79 offset:224
	ds_read_b128 v[116:119], v79 offset:240
	ds_read_b128 v[26:29], v79 offset:8416
	ds_read_b128 v[6:9], v79 offset:8432
	ds_read_b128 v[122:125], v79 offset:16608
	ds_read_b128 v[128:131], v79 offset:16624
	ds_read_b128 v[46:49], v79 offset:24800
	ds_read_b128 v[22:25], v79 offset:24816
	ds_read_b128 v[160:163], v79 offset:32992
	ds_read_b128 v[164:167], v79 offset:33008
	ds_read_b128 v[58:61], v79 offset:41184
	ds_read_b128 v[42:45], v79 offset:41200
	ds_read_b128 v[108:111], v79 offset:49376
	ds_read_b128 v[168:171], v79 offset:49392
	ds_read_b128 v[62:65], v79 offset:57568
	ds_read_b128 v[50:53], v79 offset:57584
	s_or_b32 s96, s92, s79
	s_or_b32 s40, s92, s83
	s_or_b32 s41, s92, s84
	s_or_b32 s0, s92, s87
	s_or_b32 s1, s92, s89
	s_or_b32 s3, s92, s90
	s_or_b32 s4, s92, s91
	s_or_b32 s97, s92, s80
	s_or_b32 vcc_lo, s92, s81
	s_or_b32 vcc_hi, s92, s82
	s_or_b32 s35, s92, s85
	s_or_b32 s10, s92, s86
	s_or_b32 s2, s92, s88
	v_mad_i64_i32 v[178:179], s[6:7], s96, v1, v[82:83]
	v_mov_b32_e32 v34, v149
	v_mov_b32_e32 v54, v157
	v_mov_b32_e32 v90, v144
	v_mov_b32_e32 v91, v10
	v_mov_b32_e32 v10, v145
	v_mov_b32_e32 v88, v154
	v_mov_b32_e32 v89, v20
	s_waitcnt vmcnt(1)
	v_pk_fma_f32 v[142:143], v[194:195], v[140:141], v[186:187] op_sel_hi:[1,0,1]
	v_pk_fma_f32 v[138:139], v[138:139], v[140:141], v[190:191] op_sel_hi:[1,0,1]
	v_pk_fma_f32 v[132:133], v[132:133], v[140:141], v[192:193] op_sel_hi:[1,0,1]
	v_pk_fma_f32 v[134:135], v[134:135], v[140:141], v[188:189] op_sel_hi:[1,0,1]
	global_load_dword v140, v[174:175], off nt
	v_mov_b32_e32 v20, v155
	v_mov_b32_e32 v96, v114
	s_waitcnt lgkmcnt(14)
	v_mov_b32_e32 v97, v40
	v_mov_b32_e32 v40, v115
	s_waitcnt lgkmcnt(11)
	v_mov_b32_e32 v92, v124
	s_waitcnt lgkmcnt(9)
	v_mov_b32_e32 v93, v48
	v_mov_b32_e32 v48, v125
	s_waitcnt lgkmcnt(7)
	v_mov_b32_e32 v114, v160
	s_waitcnt lgkmcnt(5)
	v_mov_b32_e32 v115, v58
	v_mov_b32_e32 v58, v161
	s_waitcnt lgkmcnt(3)
	v_mov_b32_e32 v120, v108
	s_waitcnt lgkmcnt(1)
	v_mov_b32_e32 v121, v62
	v_mov_b32_e32 v62, v109
	v_mov_b32_e32 v100, v118
	v_mov_b32_e32 v101, v8
	v_mov_b32_e32 v8, v119
	v_mov_b32_e32 v118, v128
	v_mov_b32_e32 v119, v22
	v_mov_b32_e32 v22, v129
	v_mov_b32_e32 v108, v130
	v_mov_b32_e32 v109, v24
	v_mov_b32_e32 v24, v131
	v_mov_b32_e32 v124, v164
	v_mov_b32_e32 v125, v42
	v_mov_b32_e32 v42, v165
	v_mad_i64_i32 v[128:129], s[6:7], s40, v1, v[82:83]
	v_mad_i64_i32 v[130:131], s[6:7], s41, v1, v[82:83]
	v_mad_i64_i32 v[160:161], s[6:7], s0, v1, v[82:83]
	v_mad_i64_i32 v[164:165], s[0:1], s1, v1, v[82:83]
	v_mad_i64_i32 v[180:181], s[6:7], s97, v1, v[82:83]
	v_mad_i64_i32 v[182:183], s[6:7], vcc_lo, v1, v[82:83]
	v_mad_i64_i32 v[184:185], s[6:7], vcc_hi, v1, v[82:83]
	v_mov_b32_e32 v70, v150
	v_mov_b32_e32 v84, v158
	v_mov_b32_e32 v85, v56
	v_mov_b32_e32 v56, v159
	v_mov_b32_e32 v72, v146
	v_mov_b32_e32 v73, v12
	v_mov_b32_e32 v12, v147
	v_mov_b32_e32 v94, v102
	v_mov_b32_e32 v95, v26
	v_mov_b32_e32 v26, v103
	v_mov_b32_e32 v102, v162
	v_mov_b32_e32 v103, v60
	v_mov_b32_e32 v60, v163
	v_mad_i64_i32 v[156:157], s[6:7], s35, v1, v[82:83]
	v_mad_i64_i32 v[158:159], s[6:7], s10, v1, v[82:83]
	v_mad_i64_i32 v[162:163], s[6:7], s2, v1, v[82:83]
	v_mov_b32_e32 v71, v36
	v_mov_b32_e32 v36, v151
	v_mov_b32_e32 v75, v2
	v_mov_b32_e32 v99, v18
	v_mov_b32_e32 v106, v112
	v_mov_b32_e32 v107, v38
	v_mov_b32_e32 v2, v141
	v_mov_b32_e32 v18, v153
	v_mov_b32_e32 v38, v113
	v_mov_b32_e32 v86, v104
	v_mov_b32_e32 v87, v28
	v_mov_b32_e32 v28, v105
	v_mov_b32_e32 v104, v122
	v_mov_b32_e32 v105, v46
	v_mov_b32_e32 v46, v123
	v_mov_b32_e32 v112, v110
	v_mov_b32_e32 v113, v64
	v_mov_b32_e32 v64, v111
	v_mov_b32_e32 v110, v116
	v_mov_b32_e32 v111, v6
	v_mov_b32_e32 v126, v168
	s_waitcnt vmcnt(0)
	v_pk_fma_f32 v[14:15], v[14:15], v[140:141], v[142:143] op_sel_hi:[1,0,1]
	v_pk_fma_f32 v[144:145], v[30:31], v[140:141], v[138:139] op_sel_hi:[1,0,1]
	v_mad_i64_i32 v[30:31], s[0:1], s3, v1, v[82:83]
	v_pk_fma_f32 v[154:155], v[136:137], v[152:153], v[14:15] op_sel_hi:[1,0,1]
	v_mad_i64_i32 v[14:15], s[0:1], s4, v1, v[82:83]
	v_pk_fma_f32 v[146:147], v[34:35], v[140:141], v[132:133] op_sel_hi:[1,0,1]
	v_pk_fma_f32 v[148:149], v[54:55], v[140:141], v[134:135] op_sel_hi:[1,0,1]
	global_load_dword v150, v[178:179], off nt
	global_load_dword v142, v[180:181], off nt
	global_load_dword v140, v[182:183], off nt
	global_load_dword v138, v[184:185], off nt
	global_load_dword v136, v[128:129], off nt
	global_load_dword v134, v[130:131], off nt
	global_load_dword v132, v[156:157], off nt
	s_nop 0
	global_load_dword v130, v[158:159], off nt
	global_load_dword v128, v[160:161], off nt
	global_load_dword v54, v[162:163], off nt
	global_load_dword v34, v[164:165], off nt
	s_nop 0
	global_load_dword v30, v[30:31], off nt
	s_nop 0
	global_load_dword v14, v[14:15], off nt
	v_pk_fma_f32 v[66:67], v[66:67], v[152:153], v[144:145] op_sel_hi:[1,0,1]
	v_pk_fma_f32 v[70:71], v[70:71], v[152:153], v[146:147] op_sel_hi:[1,0,1]
	v_pk_fma_f32 v[84:85], v[84:85], v[152:153], v[148:149] op_sel_hi:[1,0,1]
	s_waitcnt lgkmcnt(0)
	v_mov_b32_e32 v127, v50
	v_mov_b32_e32 v6, v117
	v_mov_b32_e32 v50, v169
	v_mov_b32_e32 v116, v166
	v_mov_b32_e32 v117, v44
	v_mov_b32_e32 v122, v170
	v_mov_b32_e32 v123, v52
	v_mov_b32_e32 v44, v167
	v_mov_b32_e32 v52, v171
	s_add_i32 s92, s92, 64
	s_cmpk_eq_i32 s92, 0x100
	s_waitcnt vmcnt(12)
	v_pk_fma_f32 v[16:17], v[16:17], v[150:151], v[154:155] op_sel_hi:[1,0,1]
	v_pk_fma_f32 v[32:33], v[32:33], v[150:151], v[66:67] op_sel_hi:[1,0,1]
	v_pk_fma_f32 v[36:37], v[36:37], v[150:151], v[70:71] op_sel_hi:[1,0,1]
	v_pk_fma_f32 v[56:57], v[56:57], v[150:151], v[84:85] op_sel_hi:[1,0,1]
	s_waitcnt vmcnt(11)
	v_pk_fma_f32 v[16:17], v[74:75], v[142:143], v[16:17] op_sel_hi:[1,0,1]
	v_pk_fma_f32 v[32:33], v[90:91], v[142:143], v[32:33] op_sel_hi:[1,0,1]
	v_pk_fma_f32 v[36:37], v[98:99], v[142:143], v[36:37] op_sel_hi:[1,0,1]
	v_pk_fma_f32 v[56:57], v[106:107], v[142:143], v[56:57] op_sel_hi:[1,0,1]
	s_waitcnt vmcnt(10)
	v_pk_fma_f32 v[2:3], v[2:3], v[140:141], v[16:17] op_sel_hi:[1,0,1]
	v_pk_fma_f32 v[10:11], v[10:11], v[140:141], v[32:33] op_sel_hi:[1,0,1]
	v_pk_fma_f32 v[16:17], v[18:19], v[140:141], v[36:37] op_sel_hi:[1,0,1]
	v_pk_fma_f32 v[18:19], v[38:39], v[140:141], v[56:57] op_sel_hi:[1,0,1]
	s_waitcnt vmcnt(9)
	v_pk_fma_f32 v[2:3], v[68:69], v[138:139], v[2:3] op_sel_hi:[1,0,1]
	v_pk_fma_f32 v[10:11], v[72:73], v[138:139], v[10:11] op_sel_hi:[1,0,1]
	v_pk_fma_f32 v[16:17], v[88:89], v[138:139], v[16:17] op_sel_hi:[1,0,1]
	v_pk_fma_f32 v[18:19], v[96:97], v[138:139], v[18:19] op_sel_hi:[1,0,1]
	s_waitcnt vmcnt(8)
	v_pk_fma_f32 v[2:3], v[4:5], v[136:137], v[2:3] op_sel_hi:[1,0,1]
	v_pk_fma_f32 v[4:5], v[12:13], v[136:137], v[10:11] op_sel_hi:[1,0,1]
	v_pk_fma_f32 v[10:11], v[20:21], v[136:137], v[16:17] op_sel_hi:[1,0,1]
	v_pk_fma_f32 v[12:13], v[40:41], v[136:137], v[18:19] op_sel_hi:[1,0,1]
	s_waitcnt vmcnt(7)
	v_pk_fma_f32 v[2:3], v[94:95], v[134:135], v[2:3] op_sel_hi:[1,0,1]
	v_pk_fma_f32 v[4:5], v[104:105], v[134:135], v[4:5] op_sel_hi:[1,0,1]
	v_pk_fma_f32 v[10:11], v[114:115], v[134:135], v[10:11] op_sel_hi:[1,0,1]
	v_pk_fma_f32 v[12:13], v[120:121], v[134:135], v[12:13] op_sel_hi:[1,0,1]
	s_waitcnt vmcnt(6)
	v_pk_fma_f32 v[2:3], v[26:27], v[132:133], v[2:3] op_sel_hi:[1,0,1]
	v_pk_fma_f32 v[4:5], v[46:47], v[132:133], v[4:5] op_sel_hi:[1,0,1]
	v_pk_fma_f32 v[10:11], v[58:59], v[132:133], v[10:11] op_sel_hi:[1,0,1]
	v_pk_fma_f32 v[12:13], v[62:63], v[132:133], v[12:13] op_sel_hi:[1,0,1]
	s_waitcnt vmcnt(5)
	v_pk_fma_f32 v[2:3], v[86:87], v[130:131], v[2:3] op_sel_hi:[1,0,1]
	v_pk_fma_f32 v[4:5], v[92:93], v[130:131], v[4:5] op_sel_hi:[1,0,1]
	v_pk_fma_f32 v[10:11], v[102:103], v[130:131], v[10:11] op_sel_hi:[1,0,1]
	v_pk_fma_f32 v[12:13], v[112:113], v[130:131], v[12:13] op_sel_hi:[1,0,1]
	s_waitcnt vmcnt(4)
	v_pk_fma_f32 v[2:3], v[28:29], v[128:129], v[2:3] op_sel_hi:[1,0,1]
	v_pk_fma_f32 v[4:5], v[48:49], v[128:129], v[4:5] op_sel_hi:[1,0,1]
	v_pk_fma_f32 v[10:11], v[60:61], v[128:129], v[10:11] op_sel_hi:[1,0,1]
	v_pk_fma_f32 v[12:13], v[64:65], v[128:129], v[12:13] op_sel_hi:[1,0,1]
	s_waitcnt vmcnt(3)
	v_pk_fma_f32 v[2:3], v[110:111], v[54:55], v[2:3] op_sel_hi:[1,0,1]
	v_pk_fma_f32 v[4:5], v[118:119], v[54:55], v[4:5] op_sel_hi:[1,0,1]
	v_pk_fma_f32 v[10:11], v[124:125], v[54:55], v[10:11] op_sel_hi:[1,0,1]
	v_pk_fma_f32 v[12:13], v[126:127], v[54:55], v[12:13] op_sel_hi:[1,0,1]
	s_waitcnt vmcnt(2)
	v_pk_fma_f32 v[2:3], v[6:7], v[34:35], v[2:3] op_sel_hi:[1,0,1]
	v_pk_fma_f32 v[4:5], v[22:23], v[34:35], v[4:5] op_sel_hi:[1,0,1]
	v_pk_fma_f32 v[6:7], v[42:43], v[34:35], v[10:11] op_sel_hi:[1,0,1]
	v_pk_fma_f32 v[10:11], v[50:51], v[34:35], v[12:13] op_sel_hi:[1,0,1]
	s_waitcnt vmcnt(1)
	v_pk_fma_f32 v[2:3], v[100:101], v[30:31], v[2:3] op_sel_hi:[1,0,1]
	v_pk_fma_f32 v[4:5], v[108:109], v[30:31], v[4:5] op_sel_hi:[1,0,1]
	v_pk_fma_f32 v[12:13], v[116:117], v[30:31], v[6:7] op_sel_hi:[1,0,1]
	v_pk_fma_f32 v[10:11], v[122:123], v[30:31], v[10:11] op_sel_hi:[1,0,1]
	s_waitcnt vmcnt(0)
	v_pk_fma_f32 v[8:9], v[8:9], v[14:15], v[2:3] op_sel_hi:[1,0,1]
	v_pk_fma_f32 v[6:7], v[24:25], v[14:15], v[4:5] op_sel_hi:[1,0,1]
	v_pk_fma_f32 v[4:5], v[44:45], v[14:15], v[12:13] op_sel_hi:[1,0,1]
	v_pk_fma_f32 v[2:3], v[52:53], v[14:15], v[10:11] op_sel_hi:[1,0,1]
	s_cbranch_scc0 .LBB0_13
	v_readlane_b32 s0, v255, 31
	v_readlane_b32 s1, v255, 32
	v_readlane_b32 s14, v255, 15
	s_add_i32 s12, s12, s14
	v_lshl_add_u64 v[10:11], v[80:81], 2, s[0:1]
	v_mad_i64_i32 v[10:11], s[0:1], s13, v77, v[10:11]
	v_add_co_u32_e32 v12, vcc, 0xc000, v10
	global_store_dword v[10:11], v8, off
	s_nop 0
	v_addc_co_u32_e32 v13, vcc, 0, v11, vcc
	v_add_co_u32_e32 v8, vcc, 0x18000, v10
	global_store_dword v[12:13], v9, off
	s_nop 0
	v_addc_co_u32_e32 v9, vcc, 0, v11, vcc
	global_store_dword v[8:9], v6, off
	v_add_co_u32_e32 v8, vcc, 0x24000, v10
	s_cmpk_gt_i32 s12, 0x5ff
	s_nop 0
	v_addc_co_u32_e32 v9, vcc, 0, v11, vcc
	v_add_co_u32_e32 v6, vcc, 0x30000, v10
	global_store_dword v[8:9], v7, off
	s_nop 0
	v_addc_co_u32_e32 v7, vcc, 0, v11, vcc
	global_store_dword v[6:7], v4, off
	v_add_co_u32_e32 v6, vcc, 0x3c000, v10
	v_readlane_b32 s15, v255, 16
	s_nop 0
	v_addc_co_u32_e32 v7, vcc, 0, v11, vcc
	v_add_co_u32_e32 v4, vcc, 0x48000, v10
	global_store_dword v[6:7], v5, off
	s_nop 0
	v_addc_co_u32_e32 v5, vcc, 0, v11, vcc
	global_store_dword v[4:5], v2, off
	v_add_co_u32_e32 v4, vcc, 0x54000, v10
	s_nop 1
	v_addc_co_u32_e32 v5, vcc, 0, v11, vcc
	global_store_dword v[4:5], v3, off
	s_cbranch_scc0 .LBB0_12

.LBB0_18:
	s_ashr_i32 s2, s3, 31
	s_lshr_b32 s2, s2, 28
	s_add_i32 s2, s3, s2
	s_ashr_i32 s24, s2, 4
	s_and_b32 s2, s2, 0xfff0
	s_sub_i32 s2, s3, s2
	s_bfe_i32 s6, s2, 0x80000
	s_bfe_u32 s6, s6, 0x2000d
	s_add_i32 s6, s2, s6
	s_bfe_i32 s7, s6, 0x80000
	s_and_b32 s6, s6, 0xfc
	s_ashr_i32 s25, s24, 31
	s_sext_i32_i16 s8, s7
	s_sub_i32 s2, s2, s6
	s_lshl_b64 s[6:7], s[24:25], 17
	s_add_u32 s6, s16, s6
	s_sext_i32_i8 s10, s2
	s_addc_u32 s7, s17, s7
	s_lshl_b32 s2, s8, 4
	s_and_b32 s22, s2, 0xffffffc0
	v_add_u32_e32 v45, s10, v16
	v_or_b32_e32 v8, s22, v2
	v_max_i32_e32 v4, 0, v45
	v_or_b32_e32 v26, 8, v8
	v_lshlrev_b32_e32 v4, 2, v4
	v_ashrrev_i32_e32 v9, 31, v8
	v_or_b32_e32 v20, 2, v8
	v_or_b32_e32 v22, 4, v8
	v_or_b32_e32 v24, 6, v8
	v_ashrrev_i32_e32 v27, 31, v26
	v_or_b32_e32 v28, 10, v8
	v_or_b32_e32 v30, 12, v8
	v_or_b32_e32 v32, 14, v8
	v_lshl_add_u64 v[10:11], s[6:7], 0, v[4:5]
	v_lshlrev_b64 v[18:19], 9, v[8:9]
	v_ashrrev_i32_e32 v21, 31, v20
	v_ashrrev_i32_e32 v23, 31, v22
	v_ashrrev_i32_e32 v25, 31, v24
	v_lshlrev_b64 v[26:27], 9, v[26:27]
	v_ashrrev_i32_e32 v29, 31, v28
	v_ashrrev_i32_e32 v31, 31, v30
	v_ashrrev_i32_e32 v33, 31, v32
	v_lshl_add_u64 v[18:19], v[10:11], 0, v[18:19]
	v_lshlrev_b64 v[20:21], 9, v[20:21]
	v_lshlrev_b64 v[22:23], 9, v[22:23]
	v_lshlrev_b64 v[24:25], 9, v[24:25]
	v_lshl_add_u64 v[26:27], v[10:11], 0, v[26:27]
	v_lshlrev_b64 v[28:29], 9, v[28:29]
	v_lshlrev_b64 v[30:31], 9, v[30:31]
	v_lshlrev_b64 v[32:33], 9, v[32:33]
	v_lshl_add_u64 v[20:21], v[10:11], 0, v[20:21]
	v_lshl_add_u64 v[22:23], v[10:11], 0, v[22:23]
	v_lshl_add_u64 v[24:25], v[10:11], 0, v[24:25]
	v_lshl_add_u64 v[28:29], v[10:11], 0, v[28:29]
	v_lshl_add_u64 v[30:31], v[10:11], 0, v[30:31]
	v_lshl_add_u64 v[32:33], v[10:11], 0, v[32:33]
	global_load_dword v62, v[18:19], off nt
	global_load_dword v44, v[20:21], off nt
	global_load_dword v43, v[22:23], off nt
	global_load_dword v42, v[24:25], off nt
	global_load_dword v41, v[26:27], off nt
	global_load_dword v39, v[28:29], off nt
	global_load_dword v37, v[30:31], off nt
	global_load_dword v35, v[32:33], off nt
	v_or_b32_e32 v26, 24, v8
	v_ashrrev_i32_e32 v27, 31, v26
	v_lshlrev_b64 v[26:27], 9, v[26:27]
	v_lshl_add_u64 v[46:47], v[10:11], 0, v[26:27]
	v_or_b32_e32 v26, 26, v8
	v_ashrrev_i32_e32 v27, 31, v26
	v_lshlrev_b64 v[26:27], 9, v[26:27]
	v_lshl_add_u64 v[48:49], v[10:11], 0, v[26:27]
	v_or_b32_e32 v26, 28, v8
	v_ashrrev_i32_e32 v27, 31, v26
	v_or_b32_e32 v18, 16, v8
	v_lshlrev_b64 v[26:27], 9, v[26:27]
	v_ashrrev_i32_e32 v19, 31, v18
	v_or_b32_e32 v20, 18, v8
	v_or_b32_e32 v22, 20, v8
	v_or_b32_e32 v24, 22, v8
	v_lshl_add_u64 v[50:51], v[10:11], 0, v[26:27]
	v_or_b32_e32 v26, 30, v8
	v_lshlrev_b64 v[18:19], 9, v[18:19]
	v_ashrrev_i32_e32 v21, 31, v20
	v_ashrrev_i32_e32 v23, 31, v22
	v_ashrrev_i32_e32 v25, 31, v24
	v_ashrrev_i32_e32 v27, 31, v26
	v_lshl_add_u64 v[18:19], v[10:11], 0, v[18:19]
	v_lshlrev_b64 v[20:21], 9, v[20:21]
	v_lshlrev_b64 v[22:23], 9, v[22:23]
	v_lshlrev_b64 v[24:25], 9, v[24:25]
	v_lshlrev_b64 v[26:27], 9, v[26:27]
	v_lshl_add_u64 v[20:21], v[10:11], 0, v[20:21]
	v_lshl_add_u64 v[22:23], v[10:11], 0, v[22:23]
	v_lshl_add_u64 v[24:25], v[10:11], 0, v[24:25]
	v_lshl_add_u64 v[52:53], v[10:11], 0, v[26:27]
	global_load_dword v40, v[18:19], off nt
	global_load_dword v38, v[20:21], off nt
	global_load_dword v36, v[22:23], off nt
	global_load_dword v34, v[24:25], off nt
	global_load_dword v33, v[46:47], off nt
	global_load_dword v31, v[48:49], off nt
	global_load_dword v29, v[50:51], off nt
	global_load_dword v27, v[52:53], off nt
	v_or_b32_e32 v18, 32, v8
	v_ashrrev_i32_e32 v19, 31, v18
	v_lshlrev_b64 v[18:19], 9, v[18:19]
	v_lshl_add_u64 v[46:47], v[10:11], 0, v[18:19]
	v_or_b32_e32 v18, 34, v8
	v_ashrrev_i32_e32 v19, 31, v18
	v_lshlrev_b64 v[18:19], 9, v[18:19]
	v_lshl_add_u64 v[48:49], v[10:11], 0, v[18:19]
	v_or_b32_e32 v18, 36, v8
	v_ashrrev_i32_e32 v19, 31, v18
	v_lshlrev_b64 v[18:19], 9, v[18:19]
	v_lshl_add_u64 v[50:51], v[10:11], 0, v[18:19]
	v_or_b32_e32 v18, 38, v8
	v_ashrrev_i32_e32 v19, 31, v18
	v_lshlrev_b64 v[18:19], 9, v[18:19]
	v_lshl_add_u64 v[52:53], v[10:11], 0, v[18:19]
	v_or_b32_e32 v18, 40, v8
	v_ashrrev_i32_e32 v19, 31, v18
	v_lshlrev_b64 v[18:19], 9, v[18:19]
	v_lshl_add_u64 v[54:55], v[10:11], 0, v[18:19]
	v_or_b32_e32 v18, 42, v8
	v_ashrrev_i32_e32 v19, 31, v18
	v_lshlrev_b64 v[18:19], 9, v[18:19]
	v_lshl_add_u64 v[56:57], v[10:11], 0, v[18:19]
	v_or_b32_e32 v18, 44, v8
	v_ashrrev_i32_e32 v19, 31, v18
	v_lshlrev_b64 v[18:19], 9, v[18:19]
	v_lshl_add_u64 v[58:59], v[10:11], 0, v[18:19]
	v_or_b32_e32 v18, 46, v8
	v_ashrrev_i32_e32 v19, 31, v18
	v_lshlrev_b64 v[18:19], 9, v[18:19]
	v_lshl_add_u64 v[60:61], v[10:11], 0, v[18:19]
	global_load_dword v32, v[46:47], off nt
	global_load_dword v30, v[48:49], off nt
	global_load_dword v28, v[50:51], off nt
	global_load_dword v26, v[52:53], off nt
	global_load_dword v25, v[54:55], off nt
	global_load_dword v23, v[56:57], off nt
	global_load_dword v21, v[58:59], off nt
	global_load_dword v19, v[60:61], off nt
	v_or_b32_e32 v46, 48, v8
	v_ashrrev_i32_e32 v47, 31, v46
	v_or_b32_e32 v48, 50, v8
	v_or_b32_e32 v50, 52, v8
	v_or_b32_e32 v52, 54, v8
	v_or_b32_e32 v54, 56, v8
	v_or_b32_e32 v56, 58, v8
	v_or_b32_e32 v58, 60, v8
	v_or_b32_e32 v60, 62, v8
	v_lshlrev_b64 v[46:47], 9, v[46:47]
	v_ashrrev_i32_e32 v49, 31, v48
	v_ashrrev_i32_e32 v51, 31, v50
	v_ashrrev_i32_e32 v53, 31, v52
	v_ashrrev_i32_e32 v55, 31, v54
	v_ashrrev_i32_e32 v57, 31, v56
	v_ashrrev_i32_e32 v59, 31, v58
	v_ashrrev_i32_e32 v61, 31, v60
	v_lshl_add_u64 v[46:47], v[10:11], 0, v[46:47]
	v_lshlrev_b64 v[48:49], 9, v[48:49]
	v_lshlrev_b64 v[50:51], 9, v[50:51]
	v_lshlrev_b64 v[52:53], 9, v[52:53]
	v_lshlrev_b64 v[54:55], 9, v[54:55]
	v_lshlrev_b64 v[56:57], 9, v[56:57]
	v_lshlrev_b64 v[58:59], 9, v[58:59]
	v_lshlrev_b64 v[60:61], 9, v[60:61]
	v_lshl_add_u64 v[48:49], v[10:11], 0, v[48:49]
	v_lshl_add_u64 v[50:51], v[10:11], 0, v[50:51]
	v_lshl_add_u64 v[52:53], v[10:11], 0, v[52:53]
	v_lshl_add_u64 v[54:55], v[10:11], 0, v[54:55]
	v_lshl_add_u64 v[56:57], v[10:11], 0, v[56:57]
	v_lshl_add_u64 v[58:59], v[10:11], 0, v[58:59]
	v_lshl_add_u64 v[60:61], v[10:11], 0, v[60:61]
	global_load_dword v24, v[46:47], off nt
	global_load_dword v22, v[48:49], off nt
	global_load_dword v20, v[50:51], off nt
	global_load_dword v18, v[52:53], off nt
	global_load_dword v11, v[54:55], off nt
	global_load_dword v10, v[56:57], off nt
	global_load_dword v7, v[58:59], off nt
	global_load_dword v4, v[60:61], off nt
	v_cmp_lt_i32_e64 s[6:7], -1, v45
	s_and_b64 vcc, exec, s[4:5]
	s_waitcnt vmcnt(31)
	v_cndmask_b32_e64 v45, 0, v62, s[6:7]
	s_cbranch_vccnz .LBB0_20
	v_lshl_add_u64 v[8:9], v[8:9], 2, s[12:13]
	global_load_dword v8, v[8:9], off nt
	s_waitcnt vmcnt(0)
	v_mul_f32_e32 v45, v45, v8
.LBB0_20:
	s_and_b64 vcc, exec, s[4:5]
	s_waitcnt vmcnt(30)
	v_cndmask_b32_e64 v8, 0, v44, s[6:7]
	ds_write_b32 v17, v45
	s_cbranch_vccnz .LBB0_22
	s_ashr_i32 s23, s22, 31
	v_lshl_add_u64 v[44:45], s[22:23], 0, v[2:3]
	v_lshl_add_u64 v[44:45], v[44:45], 2, s[12:13]
	global_load_dword v9, v[44:45], off offset:8 nt
	s_waitcnt vmcnt(0)
	v_mul_f32_e32 v8, v8, v9
.LBB0_22:
	ds_write_b32 v17, v8 offset:264
	s_and_b64 vcc, exec, s[4:5]
	s_waitcnt vmcnt(29)
	v_cndmask_b32_e64 v8, 0, v43, s[6:7]
	s_cbranch_vccnz .LBB0_24
	s_ashr_i32 s23, s22, 31
	v_lshl_add_u64 v[44:45], s[22:23], 0, v[2:3]
	v_lshl_add_u64 v[44:45], v[44:45], 2, s[12:13]
	global_load_dword v9, v[44:45], off offset:16 nt
	s_waitcnt vmcnt(0)
	v_mul_f32_e32 v8, v8, v9
.LBB0_24:
	ds_write_b32 v17, v8 offset:528
	s_and_b64 vcc, exec, s[4:5]
	s_waitcnt vmcnt(28)
	v_cndmask_b32_e64 v8, 0, v42, s[6:7]
	s_cbranch_vccnz .LBB0_26
	s_ashr_i32 s23, s22, 31
	v_lshl_add_u64 v[42:43], s[22:23], 0, v[2:3]
	v_lshl_add_u64 v[42:43], v[42:43], 2, s[12:13]
	global_load_dword v9, v[42:43], off offset:24 nt
	s_waitcnt vmcnt(0)
	v_mul_f32_e32 v8, v8, v9
.LBB0_26:
	ds_write_b32 v17, v8 offset:792
	s_and_b64 vcc, exec, s[4:5]
	s_waitcnt vmcnt(27)
	v_cndmask_b32_e64 v8, 0, v41, s[6:7]
	s_cbranch_vccnz .LBB0_28
	s_ashr_i32 s23, s22, 31
	v_lshl_add_u64 v[42:43], s[22:23], 0, v[2:3]
	v_lshl_add_u64 v[42:43], v[42:43], 2, s[12:13]
	global_load_dword v9, v[42:43], off offset:32 nt
	s_waitcnt vmcnt(0)
	v_mul_f32_e32 v8, v8, v9
.LBB0_28:
	ds_write_b32 v17, v8 offset:1056
	s_and_b64 vcc, exec, s[4:5]
	s_waitcnt vmcnt(26)
	v_cndmask_b32_e64 v8, 0, v39, s[6:7]
	s_cbranch_vccnz .LBB0_30
	s_ashr_i32 s23, s22, 31
	v_lshl_add_u64 v[42:43], s[22:23], 0, v[2:3]
	v_lshl_add_u64 v[42:43], v[42:43], 2, s[12:13]
	global_load_dword v9, v[42:43], off offset:40 nt
	s_waitcnt vmcnt(0)
	v_mul_f32_e32 v8, v8, v9
.LBB0_30:
	ds_write_b32 v17, v8 offset:1320
	s_and_b64 vcc, exec, s[4:5]
	s_waitcnt vmcnt(25)
	v_cndmask_b32_e64 v8, 0, v37, s[6:7]
	s_cbranch_vccnz .LBB0_32
	s_ashr_i32 s23, s22, 31
	v_lshl_add_u64 v[42:43], s[22:23], 0, v[2:3]
	v_lshl_add_u64 v[42:43], v[42:43], 2, s[12:13]
	global_load_dword v9, v[42:43], off offset:48 nt
	s_waitcnt vmcnt(0)
	v_mul_f32_e32 v8, v8, v9
.LBB0_32:
	ds_write_b32 v17, v8 offset:1584
	s_and_b64 vcc, exec, s[4:5]
	s_waitcnt vmcnt(24)
	v_cndmask_b32_e64 v8, 0, v35, s[6:7]
	s_cbranch_vccnz .LBB0_34
	s_ashr_i32 s23, s22, 31
	v_lshl_add_u64 v[42:43], s[22:23], 0, v[2:3]
	v_lshl_add_u64 v[42:43], v[42:43], 2, s[12:13]
	global_load_dword v9, v[42:43], off offset:56 nt
	s_waitcnt vmcnt(0)
	v_mul_f32_e32 v8, v8, v9
.LBB0_34:
	ds_write_b32 v17, v8 offset:1848
	s_and_b64 vcc, exec, s[4:5]
	s_waitcnt vmcnt(23)
	v_cndmask_b32_e64 v8, 0, v40, s[6:7]
	s_cbranch_vccnz .LBB0_36
	s_ashr_i32 s23, s22, 31
	v_lshl_add_u64 v[40:41], s[22:23], 0, v[2:3]
	v_lshl_add_u64 v[40:41], v[40:41], 2, s[12:13]
	global_load_dword v9, v[40:41], off offset:64 nt
	s_waitcnt vmcnt(0)
	v_mul_f32_e32 v8, v8, v9
.LBB0_36:
	ds_write_b32 v17, v8 offset:2112
	s_and_b64 vcc, exec, s[4:5]
	s_waitcnt vmcnt(22)
	v_cndmask_b32_e64 v8, 0, v38, s[6:7]
	s_cbranch_vccnz .LBB0_38
	s_ashr_i32 s23, s22, 31
	v_lshl_add_u64 v[38:39], s[22:23], 0, v[2:3]
	v_lshl_add_u64 v[38:39], v[38:39], 2, s[12:13]
	global_load_dword v9, v[38:39], off offset:72 nt
	s_waitcnt vmcnt(0)
	v_mul_f32_e32 v8, v8, v9
.LBB0_38:
	ds_write_b32 v17, v8 offset:2376
	s_and_b64 vcc, exec, s[4:5]
	s_waitcnt vmcnt(21)
	v_cndmask_b32_e64 v8, 0, v36, s[6:7]
	s_cbranch_vccnz .LBB0_40
	s_ashr_i32 s23, s22, 31
	v_lshl_add_u64 v[36:37], s[22:23], 0, v[2:3]
	v_lshl_add_u64 v[36:37], v[36:37], 2, s[12:13]
	global_load_dword v9, v[36:37], off offset:80 nt
	s_waitcnt vmcnt(0)
	v_mul_f32_e32 v8, v8, v9
.LBB0_40:
	ds_write_b32 v17, v8 offset:2640
	s_and_b64 vcc, exec, s[4:5]
	s_waitcnt vmcnt(20)
	v_cndmask_b32_e64 v8, 0, v34, s[6:7]
	s_cbranch_vccnz .LBB0_42
	s_ashr_i32 s23, s22, 31
	v_lshl_add_u64 v[34:35], s[22:23], 0, v[2:3]
	v_lshl_add_u64 v[34:35], v[34:35], 2, s[12:13]
	global_load_dword v9, v[34:35], off offset:88 nt
	s_waitcnt vmcnt(0)
	v_mul_f32_e32 v8, v8, v9
.LBB0_42:
	ds_write_b32 v17, v8 offset:2904
	s_and_b64 vcc, exec, s[4:5]
	s_waitcnt vmcnt(19)
	v_cndmask_b32_e64 v8, 0, v33, s[6:7]
	s_cbranch_vccnz .LBB0_44
	s_ashr_i32 s23, s22, 31
	v_lshl_add_u64 v[34:35], s[22:23], 0, v[2:3]
	v_lshl_add_u64 v[34:35], v[34:35], 2, s[12:13]
	global_load_dword v9, v[34:35], off offset:96 nt
	s_waitcnt vmcnt(0)
	v_mul_f32_e32 v8, v8, v9
.LBB0_44:
	ds_write_b32 v17, v8 offset:3168
	s_and_b64 vcc, exec, s[4:5]
	s_waitcnt vmcnt(18)
	v_cndmask_b32_e64 v8, 0, v31, s[6:7]
	s_cbranch_vccnz .LBB0_46
	s_ashr_i32 s23, s22, 31
	v_lshl_add_u64 v[34:35], s[22:23], 0, v[2:3]
	v_lshl_add_u64 v[34:35], v[34:35], 2, s[12:13]
	global_load_dword v9, v[34:35], off offset:104 nt
	s_waitcnt vmcnt(0)
	v_mul_f32_e32 v8, v8, v9
.LBB0_46:
	ds_write_b32 v17, v8 offset:3432
	s_and_b64 vcc, exec, s[4:5]
	s_waitcnt vmcnt(17)
	v_cndmask_b32_e64 v8, 0, v29, s[6:7]
	s_cbranch_vccnz .LBB0_48
	s_ashr_i32 s23, s22, 31
	v_lshl_add_u64 v[34:35], s[22:23], 0, v[2:3]
	v_lshl_add_u64 v[34:35], v[34:35], 2, s[12:13]
	global_load_dword v9, v[34:35], off offset:112 nt
	s_waitcnt vmcnt(0)
	v_mul_f32_e32 v8, v8, v9
.LBB0_48:
	ds_write_b32 v17, v8 offset:3696
	s_and_b64 vcc, exec, s[4:5]
	s_waitcnt vmcnt(16)
	v_cndmask_b32_e64 v8, 0, v27, s[6:7]
	s_cbranch_vccnz .LBB0_50
	s_ashr_i32 s23, s22, 31
	v_lshl_add_u64 v[34:35], s[22:23], 0, v[2:3]
	v_lshl_add_u64 v[34:35], v[34:35], 2, s[12:13]
	global_load_dword v9, v[34:35], off offset:120 nt
	s_waitcnt vmcnt(0)
	v_mul_f32_e32 v8, v8, v9
.LBB0_50:
	ds_write_b32 v17, v8 offset:3960
	s_and_b64 vcc, exec, s[4:5]
	s_waitcnt vmcnt(15)
	v_cndmask_b32_e64 v8, 0, v32, s[6:7]
	s_cbranch_vccnz .LBB0_52
	s_ashr_i32 s23, s22, 31
	v_lshl_add_u64 v[32:33], s[22:23], 0, v[2:3]
	v_lshl_add_u64 v[32:33], v[32:33], 2, s[12:13]
	global_load_dword v9, v[32:33], off offset:128 nt
	s_waitcnt vmcnt(0)
	v_mul_f32_e32 v8, v8, v9
.LBB0_52:
	ds_write_b32 v17, v8 offset:4224
	s_and_b64 vcc, exec, s[4:5]
	s_waitcnt vmcnt(14)
	v_cndmask_b32_e64 v8, 0, v30, s[6:7]
	s_cbranch_vccnz .LBB0_54
	s_ashr_i32 s23, s22, 31
	v_lshl_add_u64 v[30:31], s[22:23], 0, v[2:3]
	v_lshl_add_u64 v[30:31], v[30:31], 2, s[12:13]
	global_load_dword v9, v[30:31], off offset:136 nt
	s_waitcnt vmcnt(0)
	v_mul_f32_e32 v8, v8, v9
.LBB0_54:
	ds_write_b32 v17, v8 offset:4488
	s_and_b64 vcc, exec, s[4:5]
	s_waitcnt vmcnt(13)
	v_cndmask_b32_e64 v8, 0, v28, s[6:7]
	s_cbranch_vccnz .LBB0_56
	s_ashr_i32 s23, s22, 31
	v_lshl_add_u64 v[28:29], s[22:23], 0, v[2:3]
	v_lshl_add_u64 v[28:29], v[28:29], 2, s[12:13]
	global_load_dword v9, v[28:29], off offset:144 nt
	s_waitcnt vmcnt(0)
	v_mul_f32_e32 v8, v8, v9
.LBB0_56:
	ds_write_b32 v17, v8 offset:4752
	s_and_b64 vcc, exec, s[4:5]
	s_waitcnt vmcnt(12)
	v_cndmask_b32_e64 v8, 0, v26, s[6:7]
	s_cbranch_vccnz .LBB0_58
	s_ashr_i32 s23, s22, 31
	v_lshl_add_u64 v[26:27], s[22:23], 0, v[2:3]
	v_lshl_add_u64 v[26:27], v[26:27], 2, s[12:13]
	global_load_dword v9, v[26:27], off offset:152 nt
	s_waitcnt vmcnt(0)
	v_mul_f32_e32 v8, v8, v9
.LBB0_58:
	ds_write_b32 v17, v8 offset:5016
	s_and_b64 vcc, exec, s[4:5]
	s_waitcnt vmcnt(11)
	v_cndmask_b32_e64 v8, 0, v25, s[6:7]
	s_cbranch_vccnz .LBB0_60
	s_ashr_i32 s23, s22, 31
	v_lshl_add_u64 v[26:27], s[22:23], 0, v[2:3]
	v_lshl_add_u64 v[26:27], v[26:27], 2, s[12:13]
	global_load_dword v9, v[26:27], off offset:160 nt
	s_waitcnt vmcnt(0)
	v_mul_f32_e32 v8, v8, v9
.LBB0_60:
	ds_write_b32 v17, v8 offset:5280
	s_and_b64 vcc, exec, s[4:5]
	s_waitcnt vmcnt(10)
	v_cndmask_b32_e64 v8, 0, v23, s[6:7]
	s_cbranch_vccnz .LBB0_62
	s_ashr_i32 s23, s22, 31
	v_lshl_add_u64 v[26:27], s[22:23], 0, v[2:3]
	v_lshl_add_u64 v[26:27], v[26:27], 2, s[12:13]
	global_load_dword v9, v[26:27], off offset:168 nt
	s_waitcnt vmcnt(0)
	v_mul_f32_e32 v8, v8, v9
.LBB0_62:
	ds_write_b32 v17, v8 offset:5544
	s_and_b64 vcc, exec, s[4:5]
	s_waitcnt vmcnt(9)
	v_cndmask_b32_e64 v8, 0, v21, s[6:7]
	s_cbranch_vccnz .LBB0_64
	s_ashr_i32 s23, s22, 31
	v_lshl_add_u64 v[26:27], s[22:23], 0, v[2:3]
	v_lshl_add_u64 v[26:27], v[26:27], 2, s[12:13]
	global_load_dword v9, v[26:27], off offset:176 nt
	s_waitcnt vmcnt(0)
	v_mul_f32_e32 v8, v8, v9
.LBB0_64:
	ds_write_b32 v17, v8 offset:5808
	s_and_b64 vcc, exec, s[4:5]
	s_waitcnt vmcnt(8)
	v_cndmask_b32_e64 v8, 0, v19, s[6:7]
	s_cbranch_vccnz .LBB0_66
	s_ashr_i32 s23, s22, 31
	v_lshl_add_u64 v[26:27], s[22:23], 0, v[2:3]
	v_lshl_add_u64 v[26:27], v[26:27], 2, s[12:13]
	global_load_dword v9, v[26:27], off offset:184 nt
	s_waitcnt vmcnt(0)
	v_mul_f32_e32 v8, v8, v9
.LBB0_66:
	ds_write_b32 v17, v8 offset:6072
	s_and_b64 vcc, exec, s[4:5]
	s_waitcnt vmcnt(7)
	v_cndmask_b32_e64 v8, 0, v24, s[6:7]
	s_cbranch_vccnz .LBB0_68
	s_ashr_i32 s23, s22, 31
	v_lshl_add_u64 v[24:25], s[22:23], 0, v[2:3]
	v_lshl_add_u64 v[24:25], v[24:25], 2, s[12:13]
	global_load_dword v9, v[24:25], off offset:192 nt
	s_waitcnt vmcnt(0)
	v_mul_f32_e32 v8, v8, v9
.LBB0_68:
	ds_write_b32 v17, v8 offset:6336
	s_and_b64 vcc, exec, s[4:5]
	s_waitcnt vmcnt(6)
	v_cndmask_b32_e64 v8, 0, v22, s[6:7]
	s_cbranch_vccnz .LBB0_70
	s_ashr_i32 s23, s22, 31
	v_lshl_add_u64 v[22:23], s[22:23], 0, v[2:3]
	v_lshl_add_u64 v[22:23], v[22:23], 2, s[12:13]
	global_load_dword v9, v[22:23], off offset:200 nt
	s_waitcnt vmcnt(0)
	v_mul_f32_e32 v8, v8, v9
.LBB0_70:
	ds_write_b32 v17, v8 offset:6600
	s_and_b64 vcc, exec, s[4:5]
	s_waitcnt vmcnt(5)
	v_cndmask_b32_e64 v8, 0, v20, s[6:7]
	s_cbranch_vccnz .LBB0_72
	s_ashr_i32 s23, s22, 31
	v_lshl_add_u64 v[20:21], s[22:23], 0, v[2:3]
	v_lshl_add_u64 v[20:21], v[20:21], 2, s[12:13]
	global_load_dword v9, v[20:21], off offset:208 nt
	s_waitcnt vmcnt(0)
	v_mul_f32_e32 v8, v8, v9
.LBB0_72:
	ds_write_b32 v17, v8 offset:6864
	s_and_b64 vcc, exec, s[4:5]
	s_waitcnt vmcnt(4)
	v_cndmask_b32_e64 v8, 0, v18, s[6:7]
	s_cbranch_vccnz .LBB0_74
	s_ashr_i32 s23, s22, 31
	v_lshl_add_u64 v[18:19], s[22:23], 0, v[2:3]
	v_lshl_add_u64 v[18:19], v[18:19], 2, s[12:13]
	global_load_dword v9, v[18:19], off offset:216 nt
	s_waitcnt vmcnt(0)
	v_mul_f32_e32 v8, v8, v9
.LBB0_74:
	ds_write_b32 v17, v8 offset:7128
	s_and_b64 vcc, exec, s[4:5]
	s_waitcnt vmcnt(3)
	v_cndmask_b32_e64 v8, 0, v11, s[6:7]
	s_cbranch_vccnz .LBB0_76
	s_ashr_i32 s23, s22, 31
	v_lshl_add_u64 v[18:19], s[22:23], 0, v[2:3]
	v_lshl_add_u64 v[18:19], v[18:19], 2, s[12:13]
	global_load_dword v9, v[18:19], off offset:224 nt
	s_waitcnt vmcnt(0)
	v_mul_f32_e32 v8, v8, v9
.LBB0_76:
	ds_write_b32 v17, v8 offset:7392
	s_and_b64 vcc, exec, s[4:5]
	s_waitcnt vmcnt(2)
	v_cndmask_b32_e64 v8, 0, v10, s[6:7]
	s_cbranch_vccnz .LBB0_78
	s_ashr_i32 s23, s22, 31
	v_lshl_add_u64 v[10:11], s[22:23], 0, v[2:3]
	v_lshl_add_u64 v[10:11], v[10:11], 2, s[12:13]
	global_load_dword v9, v[10:11], off offset:232 nt
	s_waitcnt vmcnt(0)
	v_mul_f32_e32 v8, v8, v9
.LBB0_78:
	s_and_b64 vcc, exec, s[4:5]
	s_waitcnt vmcnt(1)
	v_cndmask_b32_e64 v7, 0, v7, s[6:7]
	ds_write_b32 v17, v8 offset:7656
	s_cbranch_vccnz .LBB0_80
	s_ashr_i32 s23, s22, 31
	v_lshl_add_u64 v[8:9], s[22:23], 0, v[2:3]
	v_lshl_add_u64 v[8:9], v[8:9], 2, s[12:13]
	global_load_dword v8, v[8:9], off offset:240 nt
	s_waitcnt vmcnt(0)
	v_mul_f32_e32 v7, v7, v8
.LBB0_80:
	s_waitcnt vmcnt(0)
	v_cndmask_b32_e64 v4, 0, v4, s[6:7]
	s_and_b64 vcc, exec, s[18:19]
	ds_write_b32 v17, v7 offset:7920
	s_cbranch_vccz .LBB0_82
	s_ashr_i32 s23, s22, 31
	v_lshl_add_u64 v[8:9], s[22:23], 0, v[2:3]
	v_lshl_add_u64 v[8:9], v[8:9], 2, s[12:13]
	global_load_dword v7, v[8:9], off offset:248 nt
	s_waitcnt vmcnt(0)
	v_mul_f32_e32 v7, v4, v7
	s_cbranch_execnz .LBB0_17
	s_branch .LBB0_83

.LBB0_93:
	v_lshrrev_b32_e32 v3, 5, v210
	v_readlane_b32 s8, v255, 12
	v_and_b32_e32 v1, 0x7c, v78
	s_add_i32 s2, s3, -4
	v_lshl_or_b32 v8, s8, 4, v3
	v_mov_b32_e32 v2, s2
	v_cmp_gt_i32_e32 vcc, s3, v1
	v_mad_u64_u32 v[4:5], s[2:3], s6, v8, 0
	v_mov_b32_e32 v6, v5
	v_mad_u64_u32 v[6:7], s[2:3], s7, v8, v[6:7]
	v_cndmask_b32_e32 v2, v2, v1, vcc
	v_mov_b32_e32 v5, v6
	s_lshl_b32 s2, s8, 13
	v_lshl_add_u64 v[4:5], v[4:5], 2, s[4:5]
	v_ashrrev_i32_e32 v3, 31, v2
	s_add_i32 s3, s2, 0
	v_lshl_add_u64 v[2:3], v[2:3], 2, v[4:5]
	s_mov_b32 m0, s3
	s_lshl_b64 s[4:5], s[6:7], 3
	s_add_i32 s10, s3, 0x400
	global_load_lds_dwordx4 v[2:3], off nt
	v_lshl_add_u64 v[2:3], v[2:3], 0, s[4:5]
	s_mov_b32 m0, s10
	s_add_i32 s11, s3, 0x800
	global_load_lds_dwordx4 v[2:3], off nt
	v_lshl_add_u64 v[2:3], v[2:3], 0, s[4:5]
	s_mov_b32 m0, s11
	s_add_i32 s14, s3, 0xc00
	global_load_lds_dwordx4 v[2:3], off nt
	v_lshl_add_u64 v[2:3], v[2:3], 0, s[4:5]
	s_mov_b32 m0, s14
	s_add_i32 s15, s3, 0x1000
	global_load_lds_dwordx4 v[2:3], off nt
	v_lshl_add_u64 v[2:3], v[2:3], 0, s[4:5]
	s_mov_b32 m0, s15
	s_add_i32 s26, s3, 0x1400
	global_load_lds_dwordx4 v[2:3], off nt
	v_lshl_add_u64 v[2:3], v[2:3], 0, s[4:5]
	s_mov_b32 m0, s26
	s_add_i32 s27, s3, 0x1800
	global_load_lds_dwordx4 v[2:3], off nt
	v_lshl_add_u64 v[2:3], v[2:3], 0, s[4:5]
	s_mov_b32 m0, s27
	s_add_i32 s28, s3, 0x1c00
	global_load_lds_dwordx4 v[2:3], off nt
	v_lshl_add_u64 v[2:3], v[2:3], 0, s[4:5]
	s_mov_b32 m0, s28
	s_load_dwordx2 s[4:5], s[38:39], 0xc0
	global_load_lds_dwordx4 v[2:3], off nt
	v_readlane_b32 s2, v255, 3
	s_add_i32 s2, s96, s2
	s_min_i32 s2, s2, s0
	s_cmpk_gt_i32 s2, 0x51f
	s_cbranch_scc0 .LBB0_97
	s_cmpk_gt_u32 s2, 0x63f
	s_cbranch_scc0 .LBB0_141
	s_add_i32 s12, s2, 0xfffff9c0
	s_and_b32 s6, s12, 0xffffff00
	s_cmpk_eq_i32 s6, 0x100
	s_movk_i32 s6, 0x68
	s_cselect_b32 s6, s6, 0x70
	s_cmpk_gt_u32 s12, 0xff
	s_cselect_b32 s6, s6, 0x48
	s_add_u32 s6, s38, s6
	s_addc_u32 s7, s39, 0
	s_load_dwordx2 s[8:9], s[6:7], 0x0
	s_lshl_b32 s6, s2, 20
	s_and_b32 s13, s6, 0xf00000
	s_load_dwordx2 s[6:7], s[38:39], 0x28
	s_waitcnt lgkmcnt(0)
	s_add_u32 s8, s8, s13
	s_addc_u32 s9, s9, 0
	s_lshl_b32 s12, s12, 5
	s_and_b32 s12, s12, 0x1e00
	s_add_u32 s12, s8, s12
	s_addc_u32 s13, s9, 0
	s_cbranch_execz .LBB0_142
	s_mov_b64 s[16:17], 0x800
	s_movk_i32 s8, 0x80
	s_cbranch_execz .LBB0_98
	s_branch .LBB0_99

.LBB0_99:
	s_add_i32 s2, s8, -4
	v_cmp_gt_i32_e32 vcc, s8, v1
	v_mad_u64_u32 v[4:5], s[8:9], s16, v8, 0
	v_mov_b32_e32 v6, v5
	v_mov_b32_e32 v2, s2
	v_mad_u64_u32 v[6:7], s[8:9], s17, v8, v[6:7]
	v_cndmask_b32_e32 v2, v2, v1, vcc
	v_mov_b32_e32 v5, v6
	v_lshl_add_u64 v[4:5], v[4:5], 2, s[12:13]
	v_ashrrev_i32_e32 v3, 31, v2
	s_add_i32 s29, s3, 0x10000
	v_lshl_add_u64 v[2:3], v[2:3], 2, v[4:5]
	s_mov_b32 m0, s29
	s_lshl_b64 s[8:9], s[16:17], 3
	global_load_lds_dwordx4 v[2:3], off nt
	v_lshl_add_u64 v[2:3], v[2:3], 0, s[8:9]
	s_add_i32 m0, s3, 0x10400
	v_mov_b32_e32 v5, 0
	global_load_lds_dwordx4 v[2:3], off nt
	v_lshl_add_u64 v[2:3], v[2:3], 0, s[8:9]
	s_add_i32 m0, s3, 0x10800
	v_lshlrev_b32_e32 v10, 3, v210
	global_load_lds_dwordx4 v[2:3], off nt
	v_lshl_add_u64 v[2:3], v[2:3], 0, s[8:9]
	s_add_i32 m0, s3, 0x10c00
	v_readlane_b32 s18, v255, 3
	global_load_lds_dwordx4 v[2:3], off nt
	v_lshl_add_u64 v[2:3], v[2:3], 0, s[8:9]
	s_add_i32 m0, s3, 0x11000
	s_mov_b32 s19, 0
	global_load_lds_dwordx4 v[2:3], off nt
	v_lshl_add_u64 v[2:3], v[2:3], 0, s[8:9]
	s_add_i32 m0, s3, 0x11400
	v_mov_b32_e32 v7, v5
	global_load_lds_dwordx4 v[2:3], off nt
	v_lshl_add_u64 v[2:3], v[2:3], 0, s[8:9]
	s_add_i32 m0, s3, 0x11800
	s_mov_b32 s31, 0x3000000
	global_load_lds_dwordx4 v[2:3], off nt
	v_lshl_add_u64 v[2:3], v[2:3], 0, s[8:9]
	s_add_i32 m0, s3, 0x11c00
	s_waitcnt lgkmcnt(0)
	s_add_u32 s16, s4, 0x4000000
	global_load_lds_dwordx4 v[2:3], off nt
	s_addc_u32 s17, s5, 0
	v_and_b32_e32 v2, 7, v0
	s_add_u32 s12, s4, 0x6000000
	v_lshlrev_b32_e32 v3, 11, v2
	v_lshlrev_b32_e32 v4, 4, v2
	v_lshrrev_b32_e32 v2, 3, v0
	v_readlane_b32 s8, v255, 12
	s_addc_u32 s13, s5, 0
	s_add_i32 s2, 0, 0x20000
	v_lshlrev_b32_e32 v6, 2, v2
	s_lshl_b32 s8, s8, 11
	v_add3_u32 v9, s2, v3, v6
	v_lshlrev_b32_e32 v6, 11, v2
	s_add_i32 s2, s2, s8
	v_or_b32_e32 v2, 0x20000, v6
	v_mov_b32_e32 v3, v5
	s_mul_i32 s8, s18, 3
	s_sub_i32 s9, 0, s18
	s_lshl_b32 s30, s18, 1
	v_add_u32_e32 v11, s3, v10
	v_add_u32_e32 v12, s2, v10
	s_movk_i32 s33, 0x68
	s_mov_b32 s35, s96
	s_mov_b32 s34, 0
	s_branch .LBB0_101
.LBB0_100:
	v_mad_u64_u32 v[16:17], s[24:25], s22, v8, 0
	s_add_i32 s2, s18, -4
	v_mov_b32_e32 v18, v17
	v_mov_b32_e32 v13, s2
	v_cmp_gt_i32_e32 vcc, s18, v1
	v_mad_u64_u32 v[18:19], s[24:25], s23, v8, v[18:19]
	s_nop 0
	v_cndmask_b32_e32 v14, v13, v1, vcc
	v_mov_b32_e32 v17, v18
	v_lshl_add_u64 v[16:17], v[16:17], 2, s[20:21]
	v_ashrrev_i32_e32 v15, 31, v14
	s_mov_b32 m0, s29
	v_lshl_add_u64 v[14:15], v[14:15], 2, v[16:17]
	s_lshl_b64 s[20:21], s[22:23], 3
	global_load_lds_dwordx4 v[14:15], off nt
	v_lshl_add_u64 v[14:15], v[14:15], 0, s[20:21]
	s_add_i32 m0, s29, 0x400
	s_add_i32 s34, s34, 2
	global_load_lds_dwordx4 v[14:15], off nt
	v_lshl_add_u64 v[14:15], v[14:15], 0, s[20:21]
	s_add_i32 m0, s29, 0x800
	s_mov_b32 s35, s36
	global_load_lds_dwordx4 v[14:15], off nt
	v_lshl_add_u64 v[14:15], v[14:15], 0, s[20:21]
	s_add_i32 m0, s29, 0xc00
	s_nop 0
	global_load_lds_dwordx4 v[14:15], off nt
	v_lshl_add_u64 v[14:15], v[14:15], 0, s[20:21]
	s_add_i32 m0, s29, 0x1000
	s_nop 0
	global_load_lds_dwordx4 v[14:15], off nt
	v_lshl_add_u64 v[14:15], v[14:15], 0, s[20:21]
	s_add_i32 m0, s29, 0x1400
	s_nop 0
	global_load_lds_dwordx4 v[14:15], off nt
	v_lshl_add_u64 v[14:15], v[14:15], 0, s[20:21]
	s_add_i32 m0, s29, 0x1800
	s_nop 0
	global_load_lds_dwordx4 v[14:15], off nt
	v_lshl_add_u64 v[14:15], v[14:15], 0, s[20:21]
	s_add_i32 m0, s29, 0x1c00
	s_cmp_ge_i32 s34, s1
	global_load_lds_dwordx4 v[14:15], off nt
	s_waitcnt lgkmcnt(0)
	s_barrier
	s_cbranch_scc1 .LBB0_135

.LBB0_118:
	v_mad_u64_u32 v[16:17], s[24:25], s22, v8, 0
	s_add_i32 s2, s18, -4
	v_mov_b32_e32 v18, v17
	v_mov_b32_e32 v13, s2
	v_cmp_gt_i32_e32 vcc, s18, v1
	v_mad_u64_u32 v[18:19], s[24:25], s23, v8, v[18:19]
	s_nop 0
	v_cndmask_b32_e32 v14, v13, v1, vcc
	v_mov_b32_e32 v17, v18
	v_lshl_add_u64 v[16:17], v[16:17], 2, s[20:21]
	v_ashrrev_i32_e32 v15, 31, v14
	s_mov_b32 m0, s3
	v_lshl_add_u64 v[14:15], v[14:15], 2, v[16:17]
	s_lshl_b64 s[20:21], s[22:23], 3
	global_load_lds_dwordx4 v[14:15], off nt
	v_lshl_add_u64 v[14:15], v[14:15], 0, s[20:21]
	s_mov_b32 m0, s10
	s_min_i32 s2, s35, s0
	global_load_lds_dwordx4 v[14:15], off nt
	v_lshl_add_u64 v[14:15], v[14:15], 0, s[20:21]
	s_mov_b32 m0, s11
	s_cmpk_gt_i32 s2, 0x51f
	global_load_lds_dwordx4 v[14:15], off nt
	v_lshl_add_u64 v[14:15], v[14:15], 0, s[20:21]
	s_mov_b32 m0, s14
	s_mov_b64 s[24:25], -1
	global_load_lds_dwordx4 v[14:15], off nt
	v_lshl_add_u64 v[14:15], v[14:15], 0, s[20:21]
	s_mov_b32 m0, s15
	s_nop 0
	global_load_lds_dwordx4 v[14:15], off nt
	v_lshl_add_u64 v[14:15], v[14:15], 0, s[20:21]
	s_mov_b32 m0, s26
	s_nop 0
	global_load_lds_dwordx4 v[14:15], off nt
	v_lshl_add_u64 v[14:15], v[14:15], 0, s[20:21]
	s_mov_b32 m0, s27
	s_nop 0
	global_load_lds_dwordx4 v[14:15], off nt
	v_lshl_add_u64 v[14:15], v[14:15], 0, s[20:21]
	s_mov_b32 m0, s28
	s_nop 0
	global_load_lds_dwordx4 v[14:15], off nt
	s_waitcnt lgkmcnt(0)
	s_barrier
	s_cbranch_scc0 .LBB0_124
	s_cmpk_gt_u32 s2, 0x63f
	s_cbranch_scc0 .LBB0_121
	s_add_i32 s20, s2, 0xfffff9c0
	s_lshl_b32 s18, s20, 3
	s_and_b32 s18, s18, 0x780
	s_and_b32 s21, s20, 0xffffff00
	s_cmpk_eq_i32 s21, 0x100
	s_cselect_b32 s21, s31, 0x3800000
	s_cmpk_gt_u32 s20, 0xff
	s_cselect_b32 s20, s21, 0x2800000
	s_add_u32 s20, s4, s20
	s_addc_u32 s21, s5, 0
	s_mov_b64 s[24:25], 0
	s_mov_b64 s[22:23], s[18:19]

.LBB0_154:
	v_and_b32_e32 v9, 0x7e, v6
	v_bfe_u32 v10, v1, 6, 7
	v_cmp_le_u32_e32 vcc, v9, v10
	v_mov_b32_e32 v3, 0
	v_ashrrev_i32_e32 v7, 31, v6
	v_mov_b32_e32 v8, 0
	s_and_saveexec_b64 s[20:21], vcc
	s_cbranch_execz .LBB0_156
	s_waitcnt lgkmcnt(0)
	v_lshl_add_u64 v[12:13], v[6:7], 2, s[6:7]
	global_load_dword v8, v[12:13], off nt
.LBB0_156:
	s_or_b64 exec, exec, s[20:21]
	v_cmp_lt_u32_e32 vcc, v9, v10
	s_and_saveexec_b64 s[20:21], vcc
	s_cbranch_execz .LBB0_153
	s_waitcnt lgkmcnt(0)
	v_lshl_add_u64 v[10:11], v[6:7], 2, s[6:7]
	global_load_dword v3, v[10:11], off offset:4 nt
	s_branch .LBB0_153

.LBB0_159:
	v_ashrrev_i32_e32 v3, 31, v2
	v_lshrrev_b32_e32 v4, 21, v3
	v_add_u32_e32 v4, v2, v4
	v_ashrrev_i32_e32 v4, 11, v4
	v_mul_i32_i24_e32 v5, 0x800, v4
	v_sub_u32_e32 v6, v2, v5
	v_ashrrev_i32_e32 v7, 31, v6
	v_lshlrev_b64 v[6:7], 7, v[6:7]
	v_ashrrev_i32_e32 v5, 31, v4
	v_lshl_add_u64 v[6:7], s[16:17], 0, v[6:7]
	v_lshl_add_u64 v[4:5], v[4:5], 2, v[6:7]
	global_load_dword v8, v[4:5], off nt
	v_lshl_add_u64 v[4:5], v[2:3], 1, s[6:7]
	v_add_co_u32_e32 v6, vcc, 0x20000, v4
	v_add_u32_e32 v2, s12, v2
	s_nop 0
	v_addc_co_u32_e32 v7, vcc, 0, v5, vcc
	v_cmp_lt_i32_e32 vcc, s0, v2
	s_waitcnt vmcnt(0)
	v_cvt_pk_bf16_f32 v3, v8, v1
	global_store_short v[4:5], v3, off
	v_lshlrev_b32_e32 v9, 16, v3
	s_or_b64 s[10:11], vcc, s[10:11]
	v_sub_f32_e32 v3, v8, v9
	v_cvt_pk_bf16_f32 v3, v3, v1
	global_store_short v[6:7], v3, off
	s_andn2_b64 exec, exec, s[10:11]
	s_cbranch_execnz .LBB0_159
